# phase5 and phase7 epilogues: residual/y loads hoisted above the preceding stores (fresh registers) with exact counted waits
# speedup vs baseline: 1.0484x; 1.0174x over previous
; #define PG8_STAGE(bufoff, gbase, voff) do { _Pragma("unroll") for (int _i = 0; _i < 2; ++_i) \
;         __builtin_amdgcn_global_load_lds((const unsigned*)((const char*)(gbase) + (voff)[_i]), (PG8_LAS unsigned*)(lds + (bufoff) + ldsw + _i * 8192), 16, 0, 0); } while (0)
; #define PG8_LDA(dst, b, h) do { _Pragma("unroll") for (int m = 0; m < 4; ++m) _Pragma("unroll") for (int k = 0; k < 2; ++k) dst[m][k] = *(const PG8_LAS bf16x8*)(lds + PG8_SA(b, h) + aoff + m * 2048 + k * 1024); } while (0)
; #define PG8_WAIT_V(n) asm volatile("s_waitcnt vmcnt(" #n ")" ::: "memory")
; #define PG8_BAR __builtin_amdgcn_s_barrier()
; template <class Epi, class Sched>
; __device__ __forceinline__ void gemm_phase(PG8_LAS unsigned char* lds, const Gemm g, const Sched& S, const Epi& E) {
;     ...
;         for (int t = 0; t < nt; t += 2) {
;             const bool last = (t == nt - 2);
;             const char* a1 = cA + (size_t)(t + 1) * kstep;
;             const char* a2 = last ? nA : cA + (size_t)(t + 2) * kstep; const char* b2 = last ? nB : cB + (size_t)(t + 2) * kstep;
;             const char* a3 = a2 + kstep; const char* b3 = b2 + kstep;
;             PG8_LDB(B0, 0, 0); PG8_SCHED; PG8_LDA(At, 0, 0); PG8_STAGE(PG8_SA(1, 1), a1 + hstep, voffA);
;             PG8_WAIT_L(8); PG8_BAR; PG8_WAIT_L(0); PG8_MMA(0, 0, At, B0); PG8_BAR; PG8_SCHED;
;             PG8_LDB(B1, 0, 1); PG8_STAGE(PG8_SB(0, 0), b2, voffB);
;             PG8_BAR; PG8_WAIT_L(0); PG8_MMA(0, 1, At, B1); PG8_BAR;
;             PG8_LDA(At, 0, 1); PG8_STAGE(PG8_SA(0, 0), a2, voffA);
;             PG8_BAR; PG8_WAIT_L(0); PG8_MMA(1, 0, At, B0); PG8_BAR; PG8_SCHED;
;             PG8_STAGE(PG8_SB(0, 1), b2 + hstep, voffB);
;             PG8_WAIT_V(6); PG8_BAR; PG8_MMA(1, 1, At, B1); PG8_BAR;
;             PG8_LDB(B0, 1, 0); PG8_SCHED; PG8_LDA(At, 1, 0); PG8_STAGE(PG8_SA(0, 1), a2 + hstep, voffA);
;             PG8_WAIT_L(8); PG8_BAR; PG8_WAIT_L(0); PG8_MMA(0, 0, At, B0); PG8_BAR; PG8_SCHED;
;             PG8_LDB(B1, 1, 1); PG8_STAGE(PG8_SB(1, 0), b3, voffB);
;             PG8_BAR; PG8_WAIT_L(0); PG8_MMA(0, 1, At, B1); PG8_BAR;
;             PG8_LDA(At, 1, 1); PG8_STAGE(PG8_SA(1, 0), a3, voffA);
;             PG8_BAR; PG8_WAIT_L(0); PG8_MMA(1, 0, At, B0); PG8_BAR; PG8_SCHED;
;             PG8_STAGE(PG8_SB(1, 1), b3 + hstep, voffB);
;             PG8_WAIT_V(6); PG8_BAR; PG8_MMA(1, 1, At, B1); PG8_BAR;
.LBB0_750:
	ds_read_b128 v[138:141], v147
	ds_read_b128 v[164:167], v148
	ds_read_b128 v[168:171], v149
	ds_read_b128 v[172:175], v150
	s_add_u32 s30, s28, 0xfffc0080
	s_addc_u32 s31, s29, -1
	s_cmp_eq_u32 s64, 12
	s_cselect_b32 s35, s17, s31
	s_cselect_b32 s34, s25, s30
	s_cselect_b32 s31, s15, s63
	s_cselect_b32 s30, s61, s62
	s_mov_b32 m0, s59
	v_lshl_add_u64 v[142:143], s[28:29], 0, v[134:135]
	ds_read_b128 v[176:179], v145
	ds_read_b128 v[180:183], v145 offset:1024
	ds_read_b128 v[184:187], v145 offset:2048
	ds_read_b128 v[188:191], v145 offset:3072
	ds_read_b128 v[192:195], v145 offset:4096
	ds_read_b128 v[196:199], v145 offset:5120
	ds_read_b128 v[200:203], v145 offset:6144
	ds_read_b128 v[204:207], v145 offset:7168
	global_load_lds_dwordx4 v[142:143], off
	v_lshl_add_u64 v[142:143], s[28:29], 0, v[136:137]
	s_mov_b32 m0, s60
	s_nop 0
	global_load_lds_dwordx4 v[142:143], off
	s_waitcnt lgkmcnt(8)
	s_barrier
	s_waitcnt lgkmcnt(0)
	s_setprio 1
	s_waitcnt lgkmcnt(0)
	v_mfma_f32_16x16x32_bf16 v[126:129], v[138:141], v[176:179], v[126:129]
	v_mfma_f32_16x16x32_bf16 v[122:125], v[168:171], v[176:179], v[122:125]
	v_mfma_f32_16x16x32_bf16 v[110:113], v[138:141], v[184:187], v[110:113]
	v_mfma_f32_16x16x32_bf16 v[106:109], v[168:171], v[184:187], v[106:109]
	v_mfma_f32_16x16x32_bf16 v[94:97], v[138:141], v[192:195], v[94:97]
	v_mfma_f32_16x16x32_bf16 v[90:93], v[168:171], v[192:195], v[90:93]
	v_mfma_f32_16x16x32_bf16 v[78:81], v[138:141], v[200:203], v[78:81]
	v_mfma_f32_16x16x32_bf16 v[74:77], v[168:171], v[200:203], v[74:77]
	v_mfma_f32_16x16x32_bf16 v[126:129], v[164:167], v[180:183], v[126:129]
	v_mfma_f32_16x16x32_bf16 v[122:125], v[172:175], v[180:183], v[122:125]
	v_mfma_f32_16x16x32_bf16 v[110:113], v[164:167], v[188:191], v[110:113]
	v_mfma_f32_16x16x32_bf16 v[106:109], v[172:175], v[188:191], v[106:109]
	v_mfma_f32_16x16x32_bf16 v[94:97], v[164:167], v[196:199], v[94:97]
	v_mfma_f32_16x16x32_bf16 v[90:93], v[172:175], v[196:199], v[90:93]
	v_mfma_f32_16x16x32_bf16 v[78:81], v[164:167], v[204:207], v[78:81]
	v_mfma_f32_16x16x32_bf16 v[74:77], v[172:175], v[204:207], v[74:77]
	s_setprio 0
	s_barrier
	s_mov_b32 m0, s27
	v_lshl_add_u64 v[142:143], s[30:31], 0, v[130:131]
	ds_read_b128 v[208:211], v151
	ds_read_b128 v[212:215], v152
	ds_read_b128 v[216:219], v153
	ds_read_b128 v[220:223], v154
	global_load_lds_dwordx4 v[142:143], off
	v_lshl_add_u64 v[224:225], s[30:31], 0, v[132:133]
	s_mov_b32 m0, s41
	s_nop 0
	global_load_lds_dwordx4 v[224:225], off
	s_barrier
	s_waitcnt lgkmcnt(0)
	s_setprio 1
	s_waitcnt lgkmcnt(0)
	v_mfma_f32_16x16x32_bf16 v[118:121], v[208:211], v[176:179], v[118:121]
	v_mfma_f32_16x16x32_bf16 v[114:117], v[216:219], v[176:179], v[114:117]
	v_mfma_f32_16x16x32_bf16 v[102:105], v[208:211], v[184:187], v[102:105]
	v_mfma_f32_16x16x32_bf16 v[98:101], v[216:219], v[184:187], v[98:101]
	v_mfma_f32_16x16x32_bf16 v[86:89], v[208:211], v[192:195], v[86:89]
	v_mfma_f32_16x16x32_bf16 v[82:85], v[216:219], v[192:195], v[82:85]
	v_mfma_f32_16x16x32_bf16 v[70:73], v[208:211], v[200:203], v[70:73]
	v_mfma_f32_16x16x32_bf16 v[66:69], v[216:219], v[200:203], v[66:69]
	v_mfma_f32_16x16x32_bf16 v[118:121], v[212:215], v[180:183], v[118:121]
	v_mfma_f32_16x16x32_bf16 v[114:117], v[220:223], v[180:183], v[114:117]
	v_mfma_f32_16x16x32_bf16 v[102:105], v[212:215], v[188:191], v[102:105]
	v_mfma_f32_16x16x32_bf16 v[98:101], v[220:223], v[188:191], v[98:101]
	v_mfma_f32_16x16x32_bf16 v[86:89], v[212:215], v[196:199], v[86:89]
	v_mfma_f32_16x16x32_bf16 v[82:85], v[220:223], v[196:199], v[82:85]
	v_mfma_f32_16x16x32_bf16 v[70:73], v[212:215], v[204:207], v[70:73]
	v_mfma_f32_16x16x32_bf16 v[66:69], v[220:223], v[204:207], v[66:69]
	s_setprio 0
	s_mov_b32 m0, s40
	v_lshl_add_u64 v[226:227], s[34:35], 0, v[130:131]
	s_barrier
	ds_read_b128 v[176:179], v145 offset:16384
	ds_read_b128 v[180:183], v145 offset:17408
	ds_read_b128 v[184:187], v145 offset:18432
	ds_read_b128 v[188:191], v145 offset:19456
	ds_read_b128 v[192:195], v145 offset:20480
	ds_read_b128 v[196:199], v145 offset:21504
	ds_read_b128 v[200:203], v145 offset:22528
	ds_read_b128 v[204:207], v145 offset:23552
	global_load_lds_dwordx4 v[226:227], off
	v_lshl_add_u64 v[228:229], s[34:35], 0, v[132:133]
	s_mov_b32 m0, s42
	s_nop 0
	global_load_lds_dwordx4 v[228:229], off
	s_barrier
	s_waitcnt lgkmcnt(0)
	s_setprio 1
	s_waitcnt lgkmcnt(0)
	v_mfma_f32_16x16x32_bf16 v[62:65], v[138:141], v[176:179], v[62:65]
	v_mfma_f32_16x16x32_bf16 v[58:61], v[168:171], v[176:179], v[58:61]
	v_mfma_f32_16x16x32_bf16 v[46:49], v[138:141], v[184:187], v[46:49]
	v_mfma_f32_16x16x32_bf16 v[42:45], v[168:171], v[184:187], v[42:45]
	v_mfma_f32_16x16x32_bf16 v[30:33], v[138:141], v[192:195], v[30:33]
	v_mfma_f32_16x16x32_bf16 v[26:29], v[168:171], v[192:195], v[26:29]
	v_mfma_f32_16x16x32_bf16 v[14:17], v[138:141], v[200:203], v[14:17]
	v_mfma_f32_16x16x32_bf16 v[10:13], v[168:171], v[200:203], v[10:13]
	v_mfma_f32_16x16x32_bf16 v[62:65], v[164:167], v[180:183], v[62:65]
	v_mfma_f32_16x16x32_bf16 v[58:61], v[172:175], v[180:183], v[58:61]
	v_mfma_f32_16x16x32_bf16 v[46:49], v[164:167], v[188:191], v[46:49]
	v_mfma_f32_16x16x32_bf16 v[42:45], v[172:175], v[188:191], v[42:45]
	v_mfma_f32_16x16x32_bf16 v[30:33], v[164:167], v[196:199], v[30:33]
	v_mfma_f32_16x16x32_bf16 v[26:29], v[172:175], v[196:199], v[26:29]
	v_mfma_f32_16x16x32_bf16 v[14:17], v[164:167], v[204:207], v[14:17]
	v_mfma_f32_16x16x32_bf16 v[10:13], v[172:175], v[204:207], v[10:13]
	s_setprio 0
	s_barrier
; #define PG8_STAGE(bufoff, gbase, voff) do { _Pragma("unroll") for (int _i = 0; _i < 2; ++_i) \
;         __builtin_amdgcn_global_load_lds((const unsigned*)((const char*)(gbase) + (voff)[_i]), (PG8_LAS unsigned*)(lds + (bufoff) + ldsw + _i * 8192), 16, 0, 0); } while (0)
; #define PG8_LDA(dst, b, h) do { _Pragma("unroll") for (int m = 0; m < 4; ++m) _Pragma("unroll") for (int k = 0; k < 2; ++k) dst[m][k] = *(const PG8_LAS bf16x8*)(lds + PG8_SA(b, h) + aoff + m * 2048 + k * 1024); } while (0)
; #define PG8_WAIT_V(n) asm volatile("s_waitcnt vmcnt(" #n ")" ::: "memory")
; #define PG8_BAR __builtin_amdgcn_s_barrier()
; template <class Epi, class Sched>
; __device__ __forceinline__ void gemm_phase(PG8_LAS unsigned char* lds, const Gemm g, const Sched& S, const Epi& E) {
;     ...
;         for (int t = 0; t < nt; t += 2) {
;             const bool last = (t == nt - 2);
;             const char* a1 = cA + (size_t)(t + 1) * kstep;
;             const char* a2 = last ? nA : cA + (size_t)(t + 2) * kstep; const char* b2 = last ? nB : cB + (size_t)(t + 2) * kstep;
;             const char* a3 = a2 + kstep; const char* b3 = b2 + kstep;
;             PG8_LDB(B0, 0, 0); PG8_SCHED; PG8_LDA(At, 0, 0); PG8_STAGE(PG8_SA(1, 1), a1 + hstep, voffA);
;             PG8_WAIT_L(8); PG8_BAR; PG8_WAIT_L(0); PG8_MMA(0, 0, At, B0); PG8_BAR; PG8_SCHED;
;             PG8_LDB(B1, 0, 1); PG8_STAGE(PG8_SB(0, 0), b2, voffB);
;             PG8_BAR; PG8_WAIT_L(0); PG8_MMA(0, 1, At, B1); PG8_BAR;
;             PG8_LDA(At, 0, 1); PG8_STAGE(PG8_SA(0, 0), a2, voffA);
;             PG8_BAR; PG8_WAIT_L(0); PG8_MMA(1, 0, At, B0); PG8_BAR; PG8_SCHED;
;             PG8_STAGE(PG8_SB(0, 1), b2 + hstep, voffB);
;             PG8_WAIT_V(6); PG8_BAR; PG8_MMA(1, 1, At, B1); PG8_BAR;
;             PG8_LDB(B0, 1, 0); PG8_SCHED; PG8_LDA(At, 1, 0); PG8_STAGE(PG8_SA(0, 1), a2 + hstep, voffA);
;             PG8_WAIT_L(8); PG8_BAR; PG8_WAIT_L(0); PG8_MMA(0, 0, At, B0); PG8_BAR; PG8_SCHED;
;             PG8_LDB(B1, 1, 1); PG8_STAGE(PG8_SB(1, 0), b3, voffB);
;             PG8_BAR; PG8_WAIT_L(0); PG8_MMA(0, 1, At, B1); PG8_BAR;
;             PG8_LDA(At, 1, 1); PG8_STAGE(PG8_SA(1, 0), a3, voffA);
;             PG8_BAR; PG8_WAIT_L(0); PG8_MMA(1, 0, At, B0); PG8_BAR; PG8_SCHED;
;             PG8_STAGE(PG8_SB(1, 1), b3 + hstep, voffB);
;             PG8_WAIT_V(6); PG8_BAR; PG8_MMA(1, 1, At, B1); PG8_BAR;
	s_add_u32 s66, s30, 0x40000
	s_addc_u32 s67, s31, 0
	s_mov_b32 m0, s43
	v_lshl_add_u64 v[138:139], s[66:67], 0, v[130:131]
	global_load_lds_dwordx4 v[138:139], off
	v_lshl_add_u64 v[138:139], s[66:67], 0, v[132:133]
	s_mov_b32 m0, s44
	s_nop 0
	global_load_lds_dwordx4 v[138:139], off
	s_waitcnt vmcnt(6)
	s_barrier
	s_setprio 1
	v_mfma_f32_16x16x32_bf16 v[54:57], v[208:211], v[176:179], v[54:57]
	v_mfma_f32_16x16x32_bf16 v[50:53], v[216:219], v[176:179], v[50:53]
	v_mfma_f32_16x16x32_bf16 v[38:41], v[208:211], v[184:187], v[38:41]
	v_mfma_f32_16x16x32_bf16 v[34:37], v[216:219], v[184:187], v[34:37]
	v_mfma_f32_16x16x32_bf16 v[22:25], v[208:211], v[192:195], v[22:25]
	v_mfma_f32_16x16x32_bf16 v[18:21], v[216:219], v[192:195], v[18:21]
	v_mfma_f32_16x16x32_bf16 v[6:9], v[208:211], v[200:203], v[6:9]
	v_mfma_f32_16x16x32_bf16 v[2:5], v[216:219], v[200:203], v[2:5]
	v_mfma_f32_16x16x32_bf16 v[54:57], v[212:215], v[180:183], v[54:57]
	v_mfma_f32_16x16x32_bf16 v[50:53], v[220:223], v[180:183], v[50:53]
	v_mfma_f32_16x16x32_bf16 v[38:41], v[212:215], v[188:191], v[38:41]
	v_mfma_f32_16x16x32_bf16 v[34:37], v[220:223], v[188:191], v[34:37]
	v_mfma_f32_16x16x32_bf16 v[22:25], v[212:215], v[196:199], v[22:25]
	v_mfma_f32_16x16x32_bf16 v[18:21], v[220:223], v[196:199], v[18:21]
	v_mfma_f32_16x16x32_bf16 v[6:9], v[212:215], v[204:207], v[6:9]
	v_mfma_f32_16x16x32_bf16 v[2:5], v[220:223], v[204:207], v[2:5]
	s_setprio 0
	s_barrier
	ds_read_b128 v[138:141], v155
	ds_read_b128 v[164:167], v156
	ds_read_b128 v[168:171], v157
	ds_read_b128 v[172:175], v158
	s_add_u32 s34, s34, 0x40000
	s_addc_u32 s35, s35, 0
	s_mov_b32 m0, s45
	v_lshl_add_u64 v[208:209], s[34:35], 0, v[130:131]
	ds_read_b128 v[176:179], v145 offset:32768
	ds_read_b128 v[180:183], v145 offset:33792
	ds_read_b128 v[184:187], v145 offset:34816
	ds_read_b128 v[188:191], v145 offset:35840
	ds_read_b128 v[192:195], v145 offset:36864
	ds_read_b128 v[196:199], v145 offset:37888
	ds_read_b128 v[200:203], v145 offset:38912
	ds_read_b128 v[204:207], v145 offset:39936
	global_load_lds_dwordx4 v[208:209], off
	v_lshl_add_u64 v[208:209], s[34:35], 0, v[132:133]
	s_mov_b32 m0, s46
	s_nop 0
	global_load_lds_dwordx4 v[208:209], off
	s_waitcnt lgkmcnt(8)
	s_barrier
	s_waitcnt lgkmcnt(0)
	s_setprio 1
	s_waitcnt lgkmcnt(0)
	v_mfma_f32_16x16x32_bf16 v[126:129], v[138:141], v[176:179], v[126:129]
	v_mfma_f32_16x16x32_bf16 v[122:125], v[168:171], v[176:179], v[122:125]
	v_mfma_f32_16x16x32_bf16 v[110:113], v[138:141], v[184:187], v[110:113]
	v_mfma_f32_16x16x32_bf16 v[106:109], v[168:171], v[184:187], v[106:109]
	v_mfma_f32_16x16x32_bf16 v[94:97], v[138:141], v[192:195], v[94:97]
	v_mfma_f32_16x16x32_bf16 v[90:93], v[168:171], v[192:195], v[90:93]
	v_mfma_f32_16x16x32_bf16 v[78:81], v[138:141], v[200:203], v[78:81]
	v_mfma_f32_16x16x32_bf16 v[74:77], v[168:171], v[200:203], v[74:77]
	v_mfma_f32_16x16x32_bf16 v[126:129], v[164:167], v[180:183], v[126:129]
	v_mfma_f32_16x16x32_bf16 v[122:125], v[172:175], v[180:183], v[122:125]
	v_mfma_f32_16x16x32_bf16 v[110:113], v[164:167], v[188:191], v[110:113]
	v_mfma_f32_16x16x32_bf16 v[106:109], v[172:175], v[188:191], v[106:109]
	v_mfma_f32_16x16x32_bf16 v[94:97], v[164:167], v[196:199], v[94:97]
	v_mfma_f32_16x16x32_bf16 v[90:93], v[172:175], v[196:199], v[90:93]
	v_mfma_f32_16x16x32_bf16 v[78:81], v[164:167], v[204:207], v[78:81]
	v_mfma_f32_16x16x32_bf16 v[74:77], v[172:175], v[204:207], v[74:77]
	s_setprio 0
	s_barrier
	s_mov_b32 m0, s47
	v_lshl_add_u64 v[142:143], v[142:143], 0, s[8:9]
	ds_read_b128 v[208:211], v159
	ds_read_b128 v[212:215], v160
	ds_read_b128 v[216:219], v161
	ds_read_b128 v[220:223], v162
	global_load_lds_dwordx4 v[142:143], off
	v_lshl_add_u64 v[142:143], v[224:225], 0, s[8:9]
	s_mov_b32 m0, s48
	s_nop 0
	global_load_lds_dwordx4 v[142:143], off
	s_barrier
	s_waitcnt lgkmcnt(0)
	s_setprio 1
	s_waitcnt lgkmcnt(0)
	v_mfma_f32_16x16x32_bf16 v[118:121], v[208:211], v[176:179], v[118:121]
	v_mfma_f32_16x16x32_bf16 v[114:117], v[216:219], v[176:179], v[114:117]
	v_mfma_f32_16x16x32_bf16 v[102:105], v[208:211], v[184:187], v[102:105]
	v_mfma_f32_16x16x32_bf16 v[98:101], v[216:219], v[184:187], v[98:101]
	v_mfma_f32_16x16x32_bf16 v[86:89], v[208:211], v[192:195], v[86:89]
	v_mfma_f32_16x16x32_bf16 v[82:85], v[216:219], v[192:195], v[82:85]
	v_mfma_f32_16x16x32_bf16 v[70:73], v[208:211], v[200:203], v[70:73]
	v_mfma_f32_16x16x32_bf16 v[66:69], v[216:219], v[200:203], v[66:69]
	v_mfma_f32_16x16x32_bf16 v[118:121], v[212:215], v[180:183], v[118:121]
	v_mfma_f32_16x16x32_bf16 v[114:117], v[220:223], v[180:183], v[114:117]
	v_mfma_f32_16x16x32_bf16 v[102:105], v[212:215], v[188:191], v[102:105]
	v_mfma_f32_16x16x32_bf16 v[98:101], v[220:223], v[188:191], v[98:101]
	v_mfma_f32_16x16x32_bf16 v[86:89], v[212:215], v[196:199], v[86:89]
	v_mfma_f32_16x16x32_bf16 v[82:85], v[220:223], v[196:199], v[82:85]
	v_mfma_f32_16x16x32_bf16 v[70:73], v[212:215], v[204:207], v[70:73]
	v_mfma_f32_16x16x32_bf16 v[66:69], v[220:223], v[204:207], v[66:69]
	s_setprio 0
	s_mov_b32 m0, s49
	v_lshl_add_u64 v[142:143], v[226:227], 0, s[8:9]
	s_barrier
	ds_read_b128 v[176:179], v145 offset:49152
	ds_read_b128 v[180:183], v145 offset:50176
	ds_read_b128 v[184:187], v145 offset:51200
	ds_read_b128 v[188:191], v145 offset:52224
	ds_read_b128 v[192:195], v145 offset:53248
	ds_read_b128 v[196:199], v145 offset:54272
	ds_read_b128 v[200:203], v145 offset:55296
	ds_read_b128 v[204:207], v145 offset:56320
	global_load_lds_dwordx4 v[142:143], off
	v_lshl_add_u64 v[142:143], v[228:229], 0, s[8:9]
	s_mov_b32 m0, s50
	s_nop 0
	global_load_lds_dwordx4 v[142:143], off
	s_barrier
; #define PG8_BAR __builtin_amdgcn_s_barrier()
; template <class Epi, class Sched>
; __device__ __forceinline__ void gemm_phase(PG8_LAS unsigned char* lds, const Gemm g, const Sched& S, const Epi& E) {
;     ...
;             PG8_LDB(B0, 0, 0); PG8_SCHED; PG8_LDA(At, 0, 0); PG8_STAGE(PG8_SA(1, 1), a1 + hstep, voffA);
;             PG8_WAIT_L(8); PG8_BAR; PG8_WAIT_L(0); PG8_MMA(0, 0, At, B0); PG8_BAR; PG8_SCHED;
;             PG8_LDB(B1, 0, 1); PG8_STAGE(PG8_SB(0, 0), b2, voffB);
;             PG8_BAR; PG8_WAIT_L(0); PG8_MMA(0, 1, At, B1); PG8_BAR;
;             PG8_LDA(At, 0, 1); PG8_STAGE(PG8_SA(0, 0), a2, voffA);
;             PG8_BAR; PG8_WAIT_L(0); PG8_MMA(1, 0, At, B0); PG8_BAR; PG8_SCHED;
;             PG8_STAGE(PG8_SB(0, 1), b2 + hstep, voffB);
;             PG8_WAIT_V(6); PG8_BAR; PG8_MMA(1, 1, At, B1); PG8_BAR;
;             PG8_LDB(B0, 1, 0); PG8_SCHED; PG8_LDA(At, 1, 0); PG8_STAGE(PG8_SA(0, 1), a2 + hstep, voffA);
;             PG8_WAIT_L(8); PG8_BAR; PG8_WAIT_L(0); PG8_MMA(0, 0, At, B0); PG8_BAR; PG8_SCHED;
;             PG8_LDB(B1, 1, 1); PG8_STAGE(PG8_SB(1, 0), b3, voffB);
;             PG8_BAR; PG8_WAIT_L(0); PG8_MMA(0, 1, At, B1); PG8_BAR;
;             PG8_LDA(At, 1, 1); PG8_STAGE(PG8_SA(1, 0), a3, voffA);
;             PG8_BAR; PG8_WAIT_L(0); PG8_MMA(1, 0, At, B0); PG8_BAR; PG8_SCHED;
;             PG8_STAGE(PG8_SB(1, 1), b3 + hstep, voffB);
;             PG8_WAIT_V(6); PG8_BAR; PG8_MMA(1, 1, At, B1); PG8_BAR;
;   __device__ __forceinline__ void operator()(const acc8_t& acc, const pg8::Unit& u, int wr, int wc, int fr, int fq) const {
;     ...
; #pragma unroll
;     for (int ai = 0; ai < 2; ai++)
; #pragma unroll
;       for (int m = 0; m < 4; m++) {
;         const int token = (int)EPI_TOKEN(u, ai, m);
;         const float* xr = xrow(p, token);
;         float ss = 0.f;
; #pragma unroll
;         for (int bj = 0; bj < 2; bj++)
; #pragma unroll
;           for (int n = 0; n < 2; n++) {
;             const int f = EPI_COL(u, bj, n);
;             const float4 xv = *(const float4*)(xr + f);
;             const float4 o = make_float4(xv.x + acc[ai][bj][m][n][0], xv.y + acc[ai][bj][m][n][1], xv.z + acc[ai][bj][m][n][2], xv.w + acc[ai][bj][m][n][3]);
;             ss += o.x * o.x + o.y * o.y + o.z * o.z + o.w * o.w;
;             *(float4*)(p.out + O_Y + (size_t)token * 1024 + f) = o;
;             uint2 ob; ob.x = pack2(o.x, o.y); ob.y = pack2(o.z, o.w);
	s_waitcnt lgkmcnt(0)
	s_setprio 1
	s_waitcnt lgkmcnt(0)
	v_mfma_f32_16x16x32_bf16 v[62:65], v[138:141], v[176:179], v[62:65]
	v_mfma_f32_16x16x32_bf16 v[58:61], v[168:171], v[176:179], v[58:61]
	v_mfma_f32_16x16x32_bf16 v[46:49], v[138:141], v[184:187], v[46:49]
	v_mfma_f32_16x16x32_bf16 v[42:45], v[168:171], v[184:187], v[42:45]
	v_mfma_f32_16x16x32_bf16 v[30:33], v[138:141], v[192:195], v[30:33]
	v_mfma_f32_16x16x32_bf16 v[26:29], v[168:171], v[192:195], v[26:29]
	v_mfma_f32_16x16x32_bf16 v[14:17], v[138:141], v[200:203], v[14:17]
	v_mfma_f32_16x16x32_bf16 v[10:13], v[168:171], v[200:203], v[10:13]
	v_mfma_f32_16x16x32_bf16 v[62:65], v[164:167], v[180:183], v[62:65]
	v_mfma_f32_16x16x32_bf16 v[58:61], v[172:175], v[180:183], v[58:61]
	v_mfma_f32_16x16x32_bf16 v[46:49], v[164:167], v[188:191], v[46:49]
	v_mfma_f32_16x16x32_bf16 v[42:45], v[172:175], v[188:191], v[42:45]
	v_mfma_f32_16x16x32_bf16 v[30:33], v[164:167], v[196:199], v[30:33]
	v_mfma_f32_16x16x32_bf16 v[26:29], v[172:175], v[196:199], v[26:29]
	v_mfma_f32_16x16x32_bf16 v[14:17], v[164:167], v[204:207], v[14:17]
	v_mfma_f32_16x16x32_bf16 v[10:13], v[172:175], v[204:207], v[10:13]
	s_setprio 0
	s_barrier
	s_add_u32 s30, s30, 0x40080
	s_addc_u32 s31, s31, 0
	s_mov_b32 m0, s51
	v_lshl_add_u64 v[138:139], s[30:31], 0, v[130:131]
	global_load_lds_dwordx4 v[138:139], off
	v_lshl_add_u64 v[138:139], s[30:31], 0, v[132:133]
	s_mov_b32 m0, s56
	s_nop 0
	global_load_lds_dwordx4 v[138:139], off
	s_waitcnt vmcnt(6)
	s_barrier
	s_setprio 1
	v_mfma_f32_16x16x32_bf16 v[54:57], v[208:211], v[176:179], v[54:57]
	v_mfma_f32_16x16x32_bf16 v[50:53], v[216:219], v[176:179], v[50:53]
	v_mfma_f32_16x16x32_bf16 v[38:41], v[208:211], v[184:187], v[38:41]
	v_mfma_f32_16x16x32_bf16 v[34:37], v[216:219], v[184:187], v[34:37]
	v_mfma_f32_16x16x32_bf16 v[22:25], v[208:211], v[192:195], v[22:25]
	v_mfma_f32_16x16x32_bf16 v[18:21], v[216:219], v[192:195], v[18:21]
	v_mfma_f32_16x16x32_bf16 v[6:9], v[208:211], v[200:203], v[6:9]
	v_mfma_f32_16x16x32_bf16 v[2:5], v[216:219], v[200:203], v[2:5]
	v_mfma_f32_16x16x32_bf16 v[54:57], v[212:215], v[180:183], v[54:57]
	v_mfma_f32_16x16x32_bf16 v[50:53], v[220:223], v[180:183], v[50:53]
	v_mfma_f32_16x16x32_bf16 v[38:41], v[212:215], v[188:191], v[38:41]
	v_mfma_f32_16x16x32_bf16 v[34:37], v[220:223], v[188:191], v[34:37]
	v_mfma_f32_16x16x32_bf16 v[22:25], v[212:215], v[196:199], v[22:25]
	v_mfma_f32_16x16x32_bf16 v[18:21], v[220:223], v[196:199], v[18:21]
	v_mfma_f32_16x16x32_bf16 v[6:9], v[212:215], v[204:207], v[6:9]
	v_mfma_f32_16x16x32_bf16 v[2:5], v[220:223], v[204:207], v[2:5]
	s_setprio 0
	s_add_i32 s64, s64, 2
	s_add_u32 s28, s28, 0x100
	s_addc_u32 s29, s29, 0
	s_add_u32 s62, s62, 0x100
	s_addc_u32 s63, s63, 0
	s_cmp_gt_u32 s64, 13
	s_barrier
	s_cbranch_scc0 .LBB0_750
	v_readlane_b32 s64, v239, 0
	v_readlane_b32 s65, v239, 1
	v_lshl_add_u32 v140, s26, 8, v144
	v_readlane_b32 s66, v239, 2
	v_readlane_b32 s67, v239, 3
	s_mov_b64 s[52:53], s[64:65]
	v_add_u32_e32 v139, 0xffff8000, v140
	v_cmp_gt_i32_e32 vcc, s57, v140
	s_mov_b64 s[54:55], s[66:67]
	v_ashrrev_i32_e32 v141, 31, v140
	v_cndmask_b32_e32 v142, v139, v140, vcc
	v_mov_b32_e32 v139, s55
	v_mov_b32_e32 v163, s53
	v_lshl_or_b32 v138, s24, 8, v146
	v_cndmask_b32_e32 v143, 0, v141, vcc
	v_cndmask_b32_e32 v165, v139, v163, vcc
	v_mov_b32_e32 v139, s54
	v_mov_b32_e32 v163, s52
	v_cndmask_b32_e32 v164, v139, v163, vcc
	v_lshlrev_b64 v[142:143], 12, v[142:143]
	v_ashrrev_i32_e32 v139, 31, v138
	v_lshl_add_u64 v[164:165], v[164:165], 0, v[142:143]
	v_lshlrev_b64 v[142:143], 2, v[138:139]
	v_lshl_add_u64 v[168:169], v[164:165], 0, v[142:143]
	global_load_dwordx4 v[164:167], v[168:169], off
	global_load_dwordx4 v[176:179], v[168:169], off offset:64
	global_load_dwordx4 v[180:183], v[168:169], off offset:512
	global_load_dwordx4 v[184:187], v[168:169], off offset:576
	v_lshlrev_b64 v[170:171], 11, v[140:141]
	v_lshlrev_b64 v[172:173], 12, v[140:141]
	v_lshl_add_u64 v[170:171], s[10:11], 0, v[170:171]
	v_lshl_add_u64 v[172:173], s[86:87], 0, v[172:173]
	v_lshl_add_u64 v[172:173], v[172:173], 0, v[142:143]
	v_lshl_add_u64 v[170:171], v[138:139], 1, v[170:171]
	v_readlane_b32 s68, v239, 4
	v_readlane_b32 s69, v239, 5
	v_readlane_b32 s70, v239, 6
	v_readlane_b32 s71, v239, 7
	v_readlane_b32 s72, v239, 8
	v_readlane_b32 s73, v239, 9
	v_readlane_b32 s74, v239, 10
	v_readlane_b32 s75, v239, 11
	v_readlane_b32 s76, v239, 12
	v_readlane_b32 s77, v239, 13
	v_readlane_b32 s78, v239, 14
	v_readlane_b32 s79, v239, 15
	s_waitcnt vmcnt(0)
;   __device__ __forceinline__ void operator()(const acc8_t& acc, const pg8::Unit& u, int wr, int wc, int fr, int fq) const {
;     ...
; #pragma unroll
;     for (int ai = 0; ai < 2; ai++)
; #pragma unroll
;       for (int m = 0; m < 4; m++) {
;         const int token = (int)EPI_TOKEN(u, ai, m);
;         const float* xr = xrow(p, token);
;         float ss = 0.f;
; #pragma unroll
;         for (int bj = 0; bj < 2; bj++)
; #pragma unroll
;           for (int n = 0; n < 2; n++) {
;             const int f = EPI_COL(u, bj, n);
;             const float4 xv = *(const float4*)(xr + f);
;             const float4 o = make_float4(xv.x + acc[ai][bj][m][n][0], xv.y + acc[ai][bj][m][n][1], xv.z + acc[ai][bj][m][n][2], xv.w + acc[ai][bj][m][n][3]);
;             ss += o.x * o.x + o.y * o.y + o.z * o.z + o.w * o.w;
;             *(float4*)(p.out + O_Y + (size_t)token * 1024 + f) = o;
;             uint2 ob; ob.x = pack2(o.x, o.y); ob.y = pack2(o.z, o.w);
;             *(uint2*)(X1B + (size_t)token * 1024 + f) = ob;
;           }
;         ss = xsum16(ss);
;         ss = xsum32(ss);
;         if (fq == 0) atomicAdd(rss + token, ss);
;       }
	v_pk_add_f32 v[126:127], v[126:127], v[164:165]
	v_pk_add_f32 v[128:129], v[128:129], v[166:167]
	v_cvt_pk_bf16_f32 v164, v126, v127
	v_cvt_pk_bf16_f32 v165, v128, v129
	global_store_dwordx4 v[172:173], v[126:129], off
	global_store_dwordx2 v[170:171], v[164:165], off
	v_mul_f32_e32 v174, v129, v129
	v_pk_add_f32 v[122:123], v[122:123], v[176:177]
	v_pk_add_f32 v[124:125], v[124:125], v[178:179]
	v_cvt_pk_bf16_f32 v164, v122, v123
	v_cvt_pk_bf16_f32 v165, v124, v125
	global_store_dwordx4 v[172:173], v[122:125], off offset:64
	global_store_dwordx2 v[170:171], v[164:165], off offset:32
	v_pk_add_f32 v[118:119], v[118:119], v[180:181]
	v_pk_add_f32 v[120:121], v[120:121], v[182:183]
	v_cvt_pk_bf16_f32 v164, v118, v119
	v_cvt_pk_bf16_f32 v165, v120, v121
	global_store_dwordx4 v[172:173], v[118:121], off offset:512
	global_store_dwordx2 v[170:171], v[164:165], off offset:256
	v_mul_f32_e32 v168, v127, v127
	v_pk_fma_f32 v[126:127], v[126:127], v[126:127], v[168:169] op_sel_hi:[1,1,0]
	v_mul_f32_e32 v168, v125, v125
	v_pk_fma_f32 v[126:127], v[128:129], v[128:129], v[126:127]
	v_mul_f32_e32 v128, v123, v123
	v_pk_fma_f32 v[122:123], v[122:123], v[122:123], v[128:129] op_sel_hi:[1,1,0]
	v_pk_add_f32 v[126:127], v[174:175], v[126:127] op_sel_hi:[0,1]
	v_pk_fma_f32 v[122:123], v[124:125], v[124:125], v[122:123]
	v_mul_f32_e32 v124, v119, v119
	v_pk_add_f32 v[122:123], v[168:169], v[122:123] op_sel_hi:[0,1]
	v_pk_fma_f32 v[118:119], v[118:119], v[118:119], v[124:125] op_sel_hi:[1,1,0]
	v_pk_add_f32 v[122:123], v[126:127], v[122:123]
	v_mul_f32_e32 v126, v121, v121
	v_pk_fma_f32 v[118:119], v[120:121], v[120:121], v[118:119]
	v_pk_add_f32 v[114:115], v[114:115], v[184:185]
	v_pk_add_f32 v[116:117], v[116:117], v[186:187]
	v_mul_f32_e32 v120, v115, v115
	v_pk_add_f32 v[118:119], v[126:127], v[118:119] op_sel_hi:[0,1]
	global_store_dwordx4 v[172:173], v[114:117], off offset:576
	v_cvt_pk_bf16_f32 v124, v114, v115
	v_pk_add_f32 v[118:119], v[122:123], v[118:119]
	v_pk_fma_f32 v[114:115], v[114:115], v[114:115], v[120:121] op_sel_hi:[1,1,0]
	v_mul_f32_e32 v122, v117, v117
	v_pk_fma_f32 v[114:115], v[116:117], v[116:117], v[114:115]
	v_cvt_pk_bf16_f32 v125, v116, v117
	v_pk_add_f32 v[114:115], v[122:123], v[114:115] op_sel_hi:[0,1]
	v_pk_add_f32 v[114:115], v[118:119], v[114:115]
	global_store_dwordx2 v[170:171], v[124:125], off offset:288
	v_mov_b32_e32 v115, v114
	s_nop 1
	v_permlane16_swap_b32_e32 v114, v115
	v_add_f32_e32 v114, v114, v115
	v_mov_b32_e32 v115, v114
	s_nop 1
	v_permlane32_swap_b32_e32 v114, v115
	s_and_saveexec_b64 s[24:25], s[4:5]
	s_cbranch_execz .LBB0_753
	v_add_f32_e32 v116, v114, v115
	v_lshl_add_u64 v[114:115], v[140:141], 2, s[12:13]
	global_atomic_add_f32 v[114:115], v116, off
.LBB0_753:
	s_or_b64 exec, exec, s[24:25]
	v_readlane_b32 s64, v239, 0
	v_readlane_b32 s65, v239, 1
	v_readlane_b32 s66, v239, 2
	v_readlane_b32 s67, v239, 3
	s_mov_b64 s[52:53], s[64:65]
	v_or_b32_e32 v114, 16, v140
	s_mov_b64 s[54:55], s[66:67]
	v_ashrrev_i32_e32 v115, 31, v114
	v_add_u32_e32 v116, 0xffff8010, v140
	v_cmp_gt_i32_e32 vcc, s57, v114
	v_mov_b32_e32 v118, s55
	v_mov_b32_e32 v119, s53
	v_cndmask_b32_e32 v117, 0, v115, vcc
	v_cndmask_b32_e32 v116, v116, v114, vcc
	v_cndmask_b32_e32 v119, v118, v119, vcc
	v_mov_b32_e32 v118, s54
	v_mov_b32_e32 v120, s52
	v_cndmask_b32_e32 v118, v118, v120, vcc
	v_lshlrev_b64 v[116:117], 12, v[116:117]
	v_lshl_add_u64 v[116:117], v[118:119], 0, v[116:117]
	v_lshl_add_u64 v[120:121], v[116:117], 0, v[142:143]
	global_load_dwordx4 v[116:119], v[120:121], off
	global_load_dwordx4 v[176:179], v[120:121], off offset:64
	global_load_dwordx4 v[180:183], v[120:121], off offset:512
	global_load_dwordx4 v[184:187], v[120:121], off offset:576
	v_lshlrev_b64 v[122:123], 11, v[114:115]
	v_lshlrev_b64 v[124:125], 12, v[114:115]
	v_lshl_add_u64 v[122:123], s[10:11], 0, v[122:123]
	v_lshl_add_u64 v[124:125], s[86:87], 0, v[124:125]
	v_lshl_add_u64 v[124:125], v[124:125], 0, v[142:143]
	v_lshl_add_u64 v[122:123], v[138:139], 1, v[122:123]
	v_readlane_b32 s68, v239, 4
	v_readlane_b32 s69, v239, 5
	v_readlane_b32 s70, v239, 6
	v_readlane_b32 s71, v239, 7
	v_readlane_b32 s72, v239, 8
	v_readlane_b32 s73, v239, 9
	v_readlane_b32 s74, v239, 10
	v_readlane_b32 s75, v239, 11
	v_readlane_b32 s76, v239, 12
	v_readlane_b32 s77, v239, 13
	v_readlane_b32 s78, v239, 14
	v_readlane_b32 s79, v239, 15
	s_waitcnt vmcnt(0)
	v_pk_add_f32 v[110:111], v[110:111], v[116:117]
	v_pk_add_f32 v[112:113], v[112:113], v[118:119]
	v_cvt_pk_bf16_f32 v116, v110, v111
	v_cvt_pk_bf16_f32 v117, v112, v113
	global_store_dwordx4 v[124:125], v[110:113], off
	global_store_dwordx2 v[122:123], v[116:117], off
	v_mul_f32_e32 v126, v113, v113
	v_pk_add_f32 v[106:107], v[106:107], v[176:177]
	v_pk_add_f32 v[108:109], v[108:109], v[178:179]
	v_cvt_pk_bf16_f32 v116, v106, v107
	v_cvt_pk_bf16_f32 v117, v108, v109
	global_store_dwordx4 v[124:125], v[106:109], off offset:64
	global_store_dwordx2 v[122:123], v[116:117], off offset:32
	v_pk_add_f32 v[102:103], v[102:103], v[180:181]
	v_pk_add_f32 v[104:105], v[104:105], v[182:183]
	v_cvt_pk_bf16_f32 v116, v102, v103
	v_cvt_pk_bf16_f32 v117, v104, v105
	global_store_dwordx4 v[124:125], v[102:105], off offset:512
	global_store_dwordx2 v[122:123], v[116:117], off offset:256
	v_mul_f32_e32 v120, v111, v111
	v_pk_fma_f32 v[110:111], v[110:111], v[110:111], v[120:121] op_sel_hi:[1,1,0]
	v_mul_f32_e32 v120, v109, v109
	v_pk_fma_f32 v[110:111], v[112:113], v[112:113], v[110:111]
	v_mul_f32_e32 v112, v107, v107
	v_pk_fma_f32 v[106:107], v[106:107], v[106:107], v[112:113] op_sel_hi:[1,1,0]
	v_pk_add_f32 v[110:111], v[126:127], v[110:111] op_sel_hi:[0,1]
	v_pk_fma_f32 v[106:107], v[108:109], v[108:109], v[106:107]
	v_mul_f32_e32 v108, v103, v103
	v_pk_add_f32 v[106:107], v[120:121], v[106:107] op_sel_hi:[0,1]
	v_pk_fma_f32 v[102:103], v[102:103], v[102:103], v[108:109] op_sel_hi:[1,1,0]
	v_pk_add_f32 v[106:107], v[110:111], v[106:107]
	v_mul_f32_e32 v110, v105, v105
	v_pk_fma_f32 v[102:103], v[104:105], v[104:105], v[102:103]
	v_pk_add_f32 v[98:99], v[98:99], v[184:185]
	v_pk_add_f32 v[100:101], v[100:101], v[186:187]
	v_mul_f32_e32 v104, v99, v99
	v_pk_add_f32 v[102:103], v[110:111], v[102:103] op_sel_hi:[0,1]
	global_store_dwordx4 v[124:125], v[98:101], off offset:576
	v_cvt_pk_bf16_f32 v108, v98, v99
	v_pk_add_f32 v[102:103], v[106:107], v[102:103]
	v_pk_fma_f32 v[98:99], v[98:99], v[98:99], v[104:105] op_sel_hi:[1,1,0]
	v_mul_f32_e32 v106, v101, v101
	v_pk_fma_f32 v[98:99], v[100:101], v[100:101], v[98:99]
	v_cvt_pk_bf16_f32 v109, v100, v101
	v_pk_add_f32 v[98:99], v[106:107], v[98:99] op_sel_hi:[0,1]
	v_pk_add_f32 v[98:99], v[102:103], v[98:99]
	global_store_dwordx2 v[122:123], v[108:109], off offset:288
	v_mov_b32_e32 v99, v98
	s_nop 1
	v_permlane16_swap_b32_e32 v98, v99
	v_add_f32_e32 v98, v98, v99
	v_mov_b32_e32 v99, v98
	s_nop 1
	v_permlane32_swap_b32_e32 v98, v99
	s_and_saveexec_b64 s[24:25], s[4:5]
	s_cbranch_execz .LBB0_755
;   __device__ __forceinline__ void operator()(const acc8_t& acc, const pg8::Unit& u, int wr, int wc, int fr, int fq) const {
;     ...
; #pragma unroll
;     for (int ai = 0; ai < 2; ai++)
; #pragma unroll
;       for (int m = 0; m < 4; m++) {
;         const int token = (int)EPI_TOKEN(u, ai, m);
;         const float* xr = xrow(p, token);
;         float ss = 0.f;
; #pragma unroll
;         for (int bj = 0; bj < 2; bj++)
; #pragma unroll
;           for (int n = 0; n < 2; n++) {
;             const int f = EPI_COL(u, bj, n);
;             const float4 xv = *(const float4*)(xr + f);
;             const float4 o = make_float4(xv.x + acc[ai][bj][m][n][0], xv.y + acc[ai][bj][m][n][1], xv.z + acc[ai][bj][m][n][2], xv.w + acc[ai][bj][m][n][3]);
;             ss += o.x * o.x + o.y * o.y + o.z * o.z + o.w * o.w;
;             *(float4*)(p.out + O_Y + (size_t)token * 1024 + f) = o;
;             uint2 ob; ob.x = pack2(o.x, o.y); ob.y = pack2(o.z, o.w);
;             *(uint2*)(X1B + (size_t)token * 1024 + f) = ob;
;           }
;         ss = xsum16(ss);
;         ss = xsum32(ss);
;         if (fq == 0) atomicAdd(rss + token, ss);
;       }
	v_add_f32_e32 v100, v98, v99
	v_lshl_add_u64 v[98:99], v[114:115], 2, s[12:13]
	global_atomic_add_f32 v[98:99], v100, off
.LBB0_755:
	s_or_b64 exec, exec, s[24:25]
	v_readlane_b32 s64, v239, 0
	v_readlane_b32 s65, v239, 1
	v_readlane_b32 s66, v239, 2
	v_readlane_b32 s67, v239, 3
	s_mov_b64 s[52:53], s[64:65]
	v_or_b32_e32 v98, 32, v140
	s_mov_b64 s[54:55], s[66:67]
	v_ashrrev_i32_e32 v99, 31, v98
	v_add_u32_e32 v100, 0xffff8020, v140
	v_cmp_gt_i32_e32 vcc, s57, v98
	v_mov_b32_e32 v102, s55
	v_mov_b32_e32 v103, s53
	v_cndmask_b32_e32 v101, 0, v99, vcc
	v_cndmask_b32_e32 v100, v100, v98, vcc
	v_cndmask_b32_e32 v103, v102, v103, vcc
	v_mov_b32_e32 v102, s54
	v_mov_b32_e32 v104, s52
	v_cndmask_b32_e32 v102, v102, v104, vcc
	v_lshlrev_b64 v[100:101], 12, v[100:101]
	v_lshl_add_u64 v[100:101], v[102:103], 0, v[100:101]
	v_lshl_add_u64 v[104:105], v[100:101], 0, v[142:143]
	global_load_dwordx4 v[100:103], v[104:105], off
	global_load_dwordx4 v[176:179], v[104:105], off offset:64
	global_load_dwordx4 v[180:183], v[104:105], off offset:512
	global_load_dwordx4 v[184:187], v[104:105], off offset:576
	v_lshlrev_b64 v[106:107], 11, v[98:99]
	v_lshlrev_b64 v[108:109], 12, v[98:99]
	v_lshl_add_u64 v[106:107], s[10:11], 0, v[106:107]
	v_lshl_add_u64 v[108:109], s[86:87], 0, v[108:109]
	v_lshl_add_u64 v[108:109], v[108:109], 0, v[142:143]
	v_lshl_add_u64 v[106:107], v[138:139], 1, v[106:107]
	v_readlane_b32 s68, v239, 4
	v_readlane_b32 s69, v239, 5
	v_readlane_b32 s70, v239, 6
	v_readlane_b32 s71, v239, 7
	v_readlane_b32 s72, v239, 8
	v_readlane_b32 s73, v239, 9
	v_readlane_b32 s74, v239, 10
	v_readlane_b32 s75, v239, 11
	v_readlane_b32 s76, v239, 12
	v_readlane_b32 s77, v239, 13
	v_readlane_b32 s78, v239, 14
	v_readlane_b32 s79, v239, 15
	s_waitcnt vmcnt(0)
	v_pk_add_f32 v[94:95], v[94:95], v[100:101]
	v_pk_add_f32 v[96:97], v[96:97], v[102:103]
	v_cvt_pk_bf16_f32 v100, v94, v95
	v_cvt_pk_bf16_f32 v101, v96, v97
	global_store_dwordx4 v[108:109], v[94:97], off
	global_store_dwordx2 v[106:107], v[100:101], off
	v_mul_f32_e32 v110, v97, v97
	v_pk_add_f32 v[90:91], v[90:91], v[176:177]
	v_pk_add_f32 v[92:93], v[92:93], v[178:179]
	v_cvt_pk_bf16_f32 v100, v90, v91
	v_cvt_pk_bf16_f32 v101, v92, v93
	global_store_dwordx4 v[108:109], v[90:93], off offset:64
	global_store_dwordx2 v[106:107], v[100:101], off offset:32
	v_pk_add_f32 v[86:87], v[86:87], v[180:181]
	v_pk_add_f32 v[88:89], v[88:89], v[182:183]
	v_cvt_pk_bf16_f32 v100, v86, v87
	v_cvt_pk_bf16_f32 v101, v88, v89
	global_store_dwordx4 v[108:109], v[86:89], off offset:512
	global_store_dwordx2 v[106:107], v[100:101], off offset:256
	v_mul_f32_e32 v104, v95, v95
	v_pk_fma_f32 v[94:95], v[94:95], v[94:95], v[104:105] op_sel_hi:[1,1,0]
	v_mul_f32_e32 v104, v93, v93
	v_pk_fma_f32 v[94:95], v[96:97], v[96:97], v[94:95]
	v_mul_f32_e32 v96, v91, v91
	v_pk_fma_f32 v[90:91], v[90:91], v[90:91], v[96:97] op_sel_hi:[1,1,0]
	v_pk_add_f32 v[94:95], v[110:111], v[94:95] op_sel_hi:[0,1]
	v_pk_fma_f32 v[90:91], v[92:93], v[92:93], v[90:91]
	v_mul_f32_e32 v92, v87, v87
	v_pk_add_f32 v[90:91], v[104:105], v[90:91] op_sel_hi:[0,1]
	v_pk_fma_f32 v[86:87], v[86:87], v[86:87], v[92:93] op_sel_hi:[1,1,0]
	v_pk_add_f32 v[90:91], v[94:95], v[90:91]
	v_mul_f32_e32 v94, v89, v89
	v_pk_fma_f32 v[86:87], v[88:89], v[88:89], v[86:87]
	v_pk_add_f32 v[82:83], v[82:83], v[184:185]
	v_pk_add_f32 v[84:85], v[84:85], v[186:187]
	v_mul_f32_e32 v88, v83, v83
	v_pk_add_f32 v[86:87], v[94:95], v[86:87] op_sel_hi:[0,1]
	global_store_dwordx4 v[108:109], v[82:85], off offset:576
	v_cvt_pk_bf16_f32 v92, v82, v83
	v_pk_add_f32 v[86:87], v[90:91], v[86:87]
	v_pk_fma_f32 v[82:83], v[82:83], v[82:83], v[88:89] op_sel_hi:[1,1,0]
	v_mul_f32_e32 v90, v85, v85
	v_pk_fma_f32 v[82:83], v[84:85], v[84:85], v[82:83]
	v_cvt_pk_bf16_f32 v93, v84, v85
	v_pk_add_f32 v[82:83], v[90:91], v[82:83] op_sel_hi:[0,1]
	v_pk_add_f32 v[82:83], v[86:87], v[82:83]
	global_store_dwordx2 v[106:107], v[92:93], off offset:288
	v_mov_b32_e32 v83, v82
	s_nop 1
	v_permlane16_swap_b32_e32 v82, v83
	v_add_f32_e32 v82, v82, v83
	v_mov_b32_e32 v83, v82
	s_nop 1
	v_permlane32_swap_b32_e32 v82, v83
	s_and_saveexec_b64 s[24:25], s[4:5]
	s_cbranch_execz .LBB0_757
	v_add_f32_e32 v84, v82, v83
	v_lshl_add_u64 v[82:83], v[98:99], 2, s[12:13]
	global_atomic_add_f32 v[82:83], v84, off
;   __device__ __forceinline__ void operator()(const acc8_t& acc, const pg8::Unit& u, int wr, int wc, int fr, int fq) const {
;     ...
; #pragma unroll
;     for (int ai = 0; ai < 2; ai++)
; #pragma unroll
;       for (int m = 0; m < 4; m++) {
;         const int token = (int)EPI_TOKEN(u, ai, m);
;         const float* xr = xrow(p, token);
;         float ss = 0.f;
; #pragma unroll
;         for (int bj = 0; bj < 2; bj++)
; #pragma unroll
;           for (int n = 0; n < 2; n++) {
;             const int f = EPI_COL(u, bj, n);
;             const float4 xv = *(const float4*)(xr + f);
;             const float4 o = make_float4(xv.x + acc[ai][bj][m][n][0], xv.y + acc[ai][bj][m][n][1], xv.z + acc[ai][bj][m][n][2], xv.w + acc[ai][bj][m][n][3]);
;             ss += o.x * o.x + o.y * o.y + o.z * o.z + o.w * o.w;
;             *(float4*)(p.out + O_Y + (size_t)token * 1024 + f) = o;
;             uint2 ob; ob.x = pack2(o.x, o.y); ob.y = pack2(o.z, o.w);
;             *(uint2*)(X1B + (size_t)token * 1024 + f) = ob;
;           }
;         ss = xsum16(ss);
;         ss = xsum32(ss);
;         if (fq == 0) atomicAdd(rss + token, ss);
;       }
.LBB0_757:
	s_or_b64 exec, exec, s[24:25]
	v_readlane_b32 s64, v239, 0
	v_readlane_b32 s65, v239, 1
	v_readlane_b32 s66, v239, 2
	v_readlane_b32 s67, v239, 3
	s_mov_b64 s[52:53], s[64:65]
	v_or_b32_e32 v82, 48, v140
	s_mov_b64 s[54:55], s[66:67]
	v_ashrrev_i32_e32 v83, 31, v82
	v_add_u32_e32 v84, 0xffff8030, v140
	v_cmp_gt_i32_e32 vcc, s57, v82
	v_mov_b32_e32 v86, s55
	v_mov_b32_e32 v87, s53
	v_cndmask_b32_e32 v85, 0, v83, vcc
	v_cndmask_b32_e32 v84, v84, v82, vcc
	v_cndmask_b32_e32 v87, v86, v87, vcc
	v_mov_b32_e32 v86, s54
	v_mov_b32_e32 v88, s52
	v_cndmask_b32_e32 v86, v86, v88, vcc
	v_lshlrev_b64 v[84:85], 12, v[84:85]
	v_lshl_add_u64 v[84:85], v[86:87], 0, v[84:85]
	v_lshl_add_u64 v[88:89], v[84:85], 0, v[142:143]
	global_load_dwordx4 v[84:87], v[88:89], off
	global_load_dwordx4 v[176:179], v[88:89], off offset:64
	global_load_dwordx4 v[180:183], v[88:89], off offset:512
	global_load_dwordx4 v[184:187], v[88:89], off offset:576
	v_lshlrev_b64 v[90:91], 11, v[82:83]
	v_lshlrev_b64 v[92:93], 12, v[82:83]
	v_lshl_add_u64 v[90:91], s[10:11], 0, v[90:91]
	v_lshl_add_u64 v[92:93], s[86:87], 0, v[92:93]
	v_lshl_add_u64 v[92:93], v[92:93], 0, v[142:143]
	v_lshl_add_u64 v[90:91], v[138:139], 1, v[90:91]
	v_readlane_b32 s68, v239, 4
	v_readlane_b32 s69, v239, 5
	v_readlane_b32 s70, v239, 6
	v_readlane_b32 s71, v239, 7
	v_readlane_b32 s72, v239, 8
	v_readlane_b32 s73, v239, 9
	v_readlane_b32 s74, v239, 10
	v_readlane_b32 s75, v239, 11
	v_readlane_b32 s76, v239, 12
	v_readlane_b32 s77, v239, 13
	v_readlane_b32 s78, v239, 14
	v_readlane_b32 s79, v239, 15
	s_waitcnt vmcnt(0)
	v_pk_add_f32 v[78:79], v[78:79], v[84:85]
	v_pk_add_f32 v[80:81], v[80:81], v[86:87]
	v_cvt_pk_bf16_f32 v84, v78, v79
	v_cvt_pk_bf16_f32 v85, v80, v81
	global_store_dwordx4 v[92:93], v[78:81], off
	global_store_dwordx2 v[90:91], v[84:85], off
	v_mul_f32_e32 v94, v81, v81
	v_pk_add_f32 v[74:75], v[74:75], v[176:177]
	v_pk_add_f32 v[76:77], v[76:77], v[178:179]
	v_cvt_pk_bf16_f32 v84, v74, v75
	v_cvt_pk_bf16_f32 v85, v76, v77
	global_store_dwordx4 v[92:93], v[74:77], off offset:64
	global_store_dwordx2 v[90:91], v[84:85], off offset:32
	v_pk_add_f32 v[70:71], v[70:71], v[180:181]
	v_pk_add_f32 v[72:73], v[72:73], v[182:183]
	v_cvt_pk_bf16_f32 v84, v70, v71
	v_cvt_pk_bf16_f32 v85, v72, v73
	global_store_dwordx4 v[92:93], v[70:73], off offset:512
	global_store_dwordx2 v[90:91], v[84:85], off offset:256
	v_mul_f32_e32 v88, v79, v79
	v_pk_fma_f32 v[78:79], v[78:79], v[78:79], v[88:89] op_sel_hi:[1,1,0]
	v_mul_f32_e32 v88, v77, v77
	v_pk_fma_f32 v[78:79], v[80:81], v[80:81], v[78:79]
	v_mul_f32_e32 v80, v75, v75
	v_pk_fma_f32 v[74:75], v[74:75], v[74:75], v[80:81] op_sel_hi:[1,1,0]
	v_pk_add_f32 v[78:79], v[94:95], v[78:79] op_sel_hi:[0,1]
	v_pk_fma_f32 v[74:75], v[76:77], v[76:77], v[74:75]
	v_mul_f32_e32 v76, v71, v71
	v_pk_add_f32 v[74:75], v[88:89], v[74:75] op_sel_hi:[0,1]
	v_pk_fma_f32 v[70:71], v[70:71], v[70:71], v[76:77] op_sel_hi:[1,1,0]
	v_pk_add_f32 v[74:75], v[78:79], v[74:75]
	v_mul_f32_e32 v78, v73, v73
	v_pk_fma_f32 v[70:71], v[72:73], v[72:73], v[70:71]
	v_pk_add_f32 v[66:67], v[66:67], v[184:185]
	v_pk_add_f32 v[68:69], v[68:69], v[186:187]
	v_mul_f32_e32 v72, v67, v67
	v_pk_add_f32 v[70:71], v[78:79], v[70:71] op_sel_hi:[0,1]
	global_store_dwordx4 v[92:93], v[66:69], off offset:576
	v_cvt_pk_bf16_f32 v76, v66, v67
	v_pk_add_f32 v[70:71], v[74:75], v[70:71]
	v_pk_fma_f32 v[66:67], v[66:67], v[66:67], v[72:73] op_sel_hi:[1,1,0]
	v_mul_f32_e32 v74, v69, v69
	v_pk_fma_f32 v[66:67], v[68:69], v[68:69], v[66:67]
	v_cvt_pk_bf16_f32 v77, v68, v69
	v_pk_add_f32 v[66:67], v[74:75], v[66:67] op_sel_hi:[0,1]
	v_pk_add_f32 v[66:67], v[70:71], v[66:67]
	global_store_dwordx2 v[90:91], v[76:77], off offset:288
	v_mov_b32_e32 v67, v66
	s_nop 1
	v_permlane16_swap_b32_e32 v66, v67
	v_add_f32_e32 v66, v66, v67
	v_mov_b32_e32 v67, v66
	s_nop 1
	v_permlane32_swap_b32_e32 v66, v67
	s_and_saveexec_b64 s[24:25], s[4:5]
	s_cbranch_execz .LBB0_759
	v_add_f32_e32 v68, v66, v67
	v_lshl_add_u64 v[66:67], v[82:83], 2, s[12:13]
	global_atomic_add_f32 v[66:67], v68, off
.LBB0_759:
	s_or_b64 exec, exec, s[24:25]
	v_readlane_b32 s64, v239, 0
	v_readlane_b32 s65, v239, 1
	v_readlane_b32 s66, v239, 2
	v_readlane_b32 s67, v239, 3
	s_mov_b64 s[52:53], s[64:65]
	v_add_u32_e32 v66, 0x80, v140
	s_mov_b64 s[54:55], s[66:67]
	v_ashrrev_i32_e32 v67, 31, v66
	v_add_u32_e32 v68, 0xffff8080, v140
	v_cmp_gt_i32_e32 vcc, s57, v66
	v_mov_b32_e32 v70, s55
	v_mov_b32_e32 v71, s53
	v_cndmask_b32_e32 v69, 0, v67, vcc
	v_cndmask_b32_e32 v68, v68, v66, vcc
	v_cndmask_b32_e32 v71, v70, v71, vcc
	v_mov_b32_e32 v70, s54
	v_mov_b32_e32 v72, s52
	v_cndmask_b32_e32 v70, v70, v72, vcc
	v_lshlrev_b64 v[68:69], 12, v[68:69]
	v_lshl_add_u64 v[68:69], v[70:71], 0, v[68:69]
	v_lshl_add_u64 v[72:73], v[68:69], 0, v[142:143]
	global_load_dwordx4 v[68:71], v[72:73], off
	global_load_dwordx4 v[176:179], v[72:73], off offset:64
	global_load_dwordx4 v[180:183], v[72:73], off offset:512
	global_load_dwordx4 v[184:187], v[72:73], off offset:576
	v_lshlrev_b64 v[74:75], 11, v[66:67]
	v_lshlrev_b64 v[76:77], 12, v[66:67]
	v_lshl_add_u64 v[74:75], s[10:11], 0, v[74:75]
	v_lshl_add_u64 v[76:77], s[86:87], 0, v[76:77]
	v_lshl_add_u64 v[76:77], v[76:77], 0, v[142:143]
	v_lshl_add_u64 v[74:75], v[138:139], 1, v[74:75]
	v_readlane_b32 s68, v239, 4
	v_readlane_b32 s69, v239, 5
	v_readlane_b32 s70, v239, 6
	v_readlane_b32 s71, v239, 7
	v_readlane_b32 s72, v239, 8
	v_readlane_b32 s73, v239, 9
	v_readlane_b32 s74, v239, 10
	v_readlane_b32 s75, v239, 11
	v_readlane_b32 s76, v239, 12
	v_readlane_b32 s77, v239, 13
	v_readlane_b32 s78, v239, 14
	v_readlane_b32 s79, v239, 15
	s_waitcnt vmcnt(0)
;   __device__ __forceinline__ void operator()(const acc8_t& acc, const pg8::Unit& u, int wr, int wc, int fr, int fq) const {
;     ...
; #pragma unroll
;     for (int ai = 0; ai < 2; ai++)
; #pragma unroll
;       for (int m = 0; m < 4; m++) {
;         const int token = (int)EPI_TOKEN(u, ai, m);
;         const float* xr = xrow(p, token);
;         float ss = 0.f;
; #pragma unroll
;         for (int bj = 0; bj < 2; bj++)
; #pragma unroll
;           for (int n = 0; n < 2; n++) {
;             const int f = EPI_COL(u, bj, n);
;             const float4 xv = *(const float4*)(xr + f);
;             const float4 o = make_float4(xv.x + acc[ai][bj][m][n][0], xv.y + acc[ai][bj][m][n][1], xv.z + acc[ai][bj][m][n][2], xv.w + acc[ai][bj][m][n][3]);
;             ss += o.x * o.x + o.y * o.y + o.z * o.z + o.w * o.w;
;             *(float4*)(p.out + O_Y + (size_t)token * 1024 + f) = o;
;             uint2 ob; ob.x = pack2(o.x, o.y); ob.y = pack2(o.z, o.w);
;             *(uint2*)(X1B + (size_t)token * 1024 + f) = ob;
;           }
;         ss = xsum16(ss);
;         ss = xsum32(ss);
;         if (fq == 0) atomicAdd(rss + token, ss);
;       }
	v_pk_add_f32 v[62:63], v[62:63], v[68:69]
	v_pk_add_f32 v[64:65], v[64:65], v[70:71]
	v_cvt_pk_bf16_f32 v68, v62, v63
	v_cvt_pk_bf16_f32 v69, v64, v65
	global_store_dwordx4 v[76:77], v[62:65], off
	global_store_dwordx2 v[74:75], v[68:69], off
	v_mul_f32_e32 v78, v65, v65
	v_pk_add_f32 v[58:59], v[58:59], v[176:177]
	v_pk_add_f32 v[60:61], v[60:61], v[178:179]
	v_cvt_pk_bf16_f32 v68, v58, v59
	v_cvt_pk_bf16_f32 v69, v60, v61
	global_store_dwordx4 v[76:77], v[58:61], off offset:64
	global_store_dwordx2 v[74:75], v[68:69], off offset:32
	v_pk_add_f32 v[54:55], v[54:55], v[180:181]
	v_pk_add_f32 v[56:57], v[56:57], v[182:183]
	v_cvt_pk_bf16_f32 v68, v54, v55
	v_cvt_pk_bf16_f32 v69, v56, v57
	global_store_dwordx4 v[76:77], v[54:57], off offset:512
	global_store_dwordx2 v[74:75], v[68:69], off offset:256
	v_mul_f32_e32 v72, v63, v63
	v_pk_fma_f32 v[62:63], v[62:63], v[62:63], v[72:73] op_sel_hi:[1,1,0]
	v_mul_f32_e32 v72, v61, v61
	v_pk_fma_f32 v[62:63], v[64:65], v[64:65], v[62:63]
	v_mul_f32_e32 v64, v59, v59
	v_pk_fma_f32 v[58:59], v[58:59], v[58:59], v[64:65] op_sel_hi:[1,1,0]
	v_pk_add_f32 v[62:63], v[78:79], v[62:63] op_sel_hi:[0,1]
	v_pk_fma_f32 v[58:59], v[60:61], v[60:61], v[58:59]
	v_mul_f32_e32 v60, v55, v55
	v_pk_add_f32 v[58:59], v[72:73], v[58:59] op_sel_hi:[0,1]
	v_pk_fma_f32 v[54:55], v[54:55], v[54:55], v[60:61] op_sel_hi:[1,1,0]
	v_pk_add_f32 v[58:59], v[62:63], v[58:59]
	v_mul_f32_e32 v62, v57, v57
	v_pk_fma_f32 v[54:55], v[56:57], v[56:57], v[54:55]
	v_pk_add_f32 v[50:51], v[50:51], v[184:185]
	v_pk_add_f32 v[52:53], v[52:53], v[186:187]
	v_mul_f32_e32 v56, v51, v51
	v_pk_add_f32 v[54:55], v[62:63], v[54:55] op_sel_hi:[0,1]
	global_store_dwordx4 v[76:77], v[50:53], off offset:576
	v_cvt_pk_bf16_f32 v60, v50, v51
	v_pk_add_f32 v[54:55], v[58:59], v[54:55]
	v_pk_fma_f32 v[50:51], v[50:51], v[50:51], v[56:57] op_sel_hi:[1,1,0]
	v_mul_f32_e32 v58, v53, v53
	v_pk_fma_f32 v[50:51], v[52:53], v[52:53], v[50:51]
	v_cvt_pk_bf16_f32 v61, v52, v53
	v_pk_add_f32 v[50:51], v[58:59], v[50:51] op_sel_hi:[0,1]
	v_pk_add_f32 v[50:51], v[54:55], v[50:51]
	global_store_dwordx2 v[74:75], v[60:61], off offset:288
	v_mov_b32_e32 v51, v50
	s_nop 1
	v_permlane16_swap_b32_e32 v50, v51
	v_add_f32_e32 v50, v50, v51
	v_mov_b32_e32 v51, v50
	s_nop 1
	v_permlane32_swap_b32_e32 v50, v51
	s_and_saveexec_b64 s[24:25], s[4:5]
	s_cbranch_execz .LBB0_761
	v_add_f32_e32 v52, v50, v51
	v_lshl_add_u64 v[50:51], v[66:67], 2, s[12:13]
	global_atomic_add_f32 v[50:51], v52, off
.LBB0_761:
	s_or_b64 exec, exec, s[24:25]
	v_readlane_b32 s64, v239, 0
	v_readlane_b32 s65, v239, 1
	v_readlane_b32 s66, v239, 2
	v_readlane_b32 s67, v239, 3
	s_mov_b64 s[52:53], s[64:65]
	v_add_u32_e32 v50, 0x90, v140
	s_mov_b64 s[54:55], s[66:67]
	v_ashrrev_i32_e32 v51, 31, v50
	v_add_u32_e32 v52, 0xffff8090, v140
	v_cmp_gt_i32_e32 vcc, s57, v50
	v_mov_b32_e32 v54, s55
	v_mov_b32_e32 v55, s53
	v_cndmask_b32_e32 v53, 0, v51, vcc
	v_cndmask_b32_e32 v52, v52, v50, vcc
	v_cndmask_b32_e32 v55, v54, v55, vcc
	v_mov_b32_e32 v54, s54
	v_mov_b32_e32 v56, s52
	v_cndmask_b32_e32 v54, v54, v56, vcc
	v_lshlrev_b64 v[52:53], 12, v[52:53]
	v_lshl_add_u64 v[52:53], v[54:55], 0, v[52:53]
	v_lshl_add_u64 v[56:57], v[52:53], 0, v[142:143]
	global_load_dwordx4 v[52:55], v[56:57], off
	global_load_dwordx4 v[176:179], v[56:57], off offset:64
	global_load_dwordx4 v[180:183], v[56:57], off offset:512
	global_load_dwordx4 v[184:187], v[56:57], off offset:576
	v_lshlrev_b64 v[58:59], 11, v[50:51]
	v_lshlrev_b64 v[60:61], 12, v[50:51]
	v_lshl_add_u64 v[58:59], s[10:11], 0, v[58:59]
	v_lshl_add_u64 v[60:61], s[86:87], 0, v[60:61]
	v_lshl_add_u64 v[60:61], v[60:61], 0, v[142:143]
	v_lshl_add_u64 v[58:59], v[138:139], 1, v[58:59]
	v_readlane_b32 s68, v239, 4
	v_readlane_b32 s69, v239, 5
	v_readlane_b32 s70, v239, 6
	v_readlane_b32 s71, v239, 7
	v_readlane_b32 s72, v239, 8
	v_readlane_b32 s73, v239, 9
	v_readlane_b32 s74, v239, 10
	v_readlane_b32 s75, v239, 11
	v_readlane_b32 s76, v239, 12
	v_readlane_b32 s77, v239, 13
	v_readlane_b32 s78, v239, 14
	v_readlane_b32 s79, v239, 15
	s_waitcnt vmcnt(0)
	v_pk_add_f32 v[46:47], v[46:47], v[52:53]
	v_pk_add_f32 v[48:49], v[48:49], v[54:55]
	v_cvt_pk_bf16_f32 v52, v46, v47
	v_cvt_pk_bf16_f32 v53, v48, v49
	global_store_dwordx4 v[60:61], v[46:49], off
	global_store_dwordx2 v[58:59], v[52:53], off
	v_mul_f32_e32 v62, v49, v49
	v_pk_add_f32 v[42:43], v[42:43], v[176:177]
	v_pk_add_f32 v[44:45], v[44:45], v[178:179]
	v_cvt_pk_bf16_f32 v52, v42, v43
	v_cvt_pk_bf16_f32 v53, v44, v45
	global_store_dwordx4 v[60:61], v[42:45], off offset:64
	global_store_dwordx2 v[58:59], v[52:53], off offset:32
	v_pk_add_f32 v[38:39], v[38:39], v[180:181]
	v_pk_add_f32 v[40:41], v[40:41], v[182:183]
	v_cvt_pk_bf16_f32 v52, v38, v39
	v_cvt_pk_bf16_f32 v53, v40, v41
	global_store_dwordx4 v[60:61], v[38:41], off offset:512
	global_store_dwordx2 v[58:59], v[52:53], off offset:256
	v_mul_f32_e32 v56, v47, v47
	v_pk_fma_f32 v[46:47], v[46:47], v[46:47], v[56:57] op_sel_hi:[1,1,0]
	v_mul_f32_e32 v56, v45, v45
	v_pk_fma_f32 v[46:47], v[48:49], v[48:49], v[46:47]
	v_mul_f32_e32 v48, v43, v43
	v_pk_fma_f32 v[42:43], v[42:43], v[42:43], v[48:49] op_sel_hi:[1,1,0]
	v_pk_add_f32 v[46:47], v[62:63], v[46:47] op_sel_hi:[0,1]
	v_pk_fma_f32 v[42:43], v[44:45], v[44:45], v[42:43]
	v_mul_f32_e32 v44, v39, v39
	v_pk_add_f32 v[42:43], v[56:57], v[42:43] op_sel_hi:[0,1]
	v_pk_fma_f32 v[38:39], v[38:39], v[38:39], v[44:45] op_sel_hi:[1,1,0]
	v_pk_add_f32 v[42:43], v[46:47], v[42:43]
	v_mul_f32_e32 v46, v41, v41
	v_pk_fma_f32 v[38:39], v[40:41], v[40:41], v[38:39]
	v_pk_add_f32 v[34:35], v[34:35], v[184:185]
	v_pk_add_f32 v[36:37], v[36:37], v[186:187]
	v_mul_f32_e32 v40, v35, v35
	v_pk_add_f32 v[38:39], v[46:47], v[38:39] op_sel_hi:[0,1]
	global_store_dwordx4 v[60:61], v[34:37], off offset:576
	v_cvt_pk_bf16_f32 v44, v34, v35
	v_pk_add_f32 v[38:39], v[42:43], v[38:39]
	v_pk_fma_f32 v[34:35], v[34:35], v[34:35], v[40:41] op_sel_hi:[1,1,0]
	v_mul_f32_e32 v42, v37, v37
	v_pk_fma_f32 v[34:35], v[36:37], v[36:37], v[34:35]
	v_cvt_pk_bf16_f32 v45, v36, v37
	v_pk_add_f32 v[34:35], v[42:43], v[34:35] op_sel_hi:[0,1]
	v_pk_add_f32 v[34:35], v[38:39], v[34:35]
	global_store_dwordx2 v[58:59], v[44:45], off offset:288
	v_mov_b32_e32 v35, v34
	s_nop 1
	v_permlane16_swap_b32_e32 v34, v35
	v_add_f32_e32 v34, v34, v35
	v_mov_b32_e32 v35, v34
	s_nop 1
	v_permlane32_swap_b32_e32 v34, v35
	s_and_saveexec_b64 s[24:25], s[4:5]
	s_cbranch_execz .LBB0_763
	v_add_f32_e32 v36, v34, v35
	v_lshl_add_u64 v[34:35], v[50:51], 2, s[12:13]
	global_atomic_add_f32 v[34:35], v36, off
;   __device__ __forceinline__ void operator()(const acc8_t& acc, const pg8::Unit& u, int wr, int wc, int fr, int fq) const {
;     ...
; #pragma unroll
;     for (int ai = 0; ai < 2; ai++)
; #pragma unroll
;       for (int m = 0; m < 4; m++) {
;         const int token = (int)EPI_TOKEN(u, ai, m);
;         const float* xr = xrow(p, token);
;         float ss = 0.f;
; #pragma unroll
;         for (int bj = 0; bj < 2; bj++)
; #pragma unroll
;           for (int n = 0; n < 2; n++) {
;             const int f = EPI_COL(u, bj, n);
;             const float4 xv = *(const float4*)(xr + f);
;             const float4 o = make_float4(xv.x + acc[ai][bj][m][n][0], xv.y + acc[ai][bj][m][n][1], xv.z + acc[ai][bj][m][n][2], xv.w + acc[ai][bj][m][n][3]);
;             ss += o.x * o.x + o.y * o.y + o.z * o.z + o.w * o.w;
;             *(float4*)(p.out + O_Y + (size_t)token * 1024 + f) = o;
;             uint2 ob; ob.x = pack2(o.x, o.y); ob.y = pack2(o.z, o.w);
;             *(uint2*)(X1B + (size_t)token * 1024 + f) = ob;
;           }
;         ss = xsum16(ss);
;         ss = xsum32(ss);
;         if (fq == 0) atomicAdd(rss + token, ss);
;       }
.LBB0_763:
	s_or_b64 exec, exec, s[24:25]
	v_readlane_b32 s64, v239, 0
	v_readlane_b32 s65, v239, 1
	v_readlane_b32 s66, v239, 2
	v_readlane_b32 s67, v239, 3
	s_mov_b64 s[52:53], s[64:65]
	v_add_u32_e32 v34, 0xa0, v140
	s_mov_b64 s[54:55], s[66:67]
	v_ashrrev_i32_e32 v35, 31, v34
	v_add_u32_e32 v36, 0xffff80a0, v140
	v_cmp_gt_i32_e32 vcc, s57, v34
	v_mov_b32_e32 v38, s55
	v_mov_b32_e32 v39, s53
	v_cndmask_b32_e32 v37, 0, v35, vcc
	v_cndmask_b32_e32 v36, v36, v34, vcc
	v_cndmask_b32_e32 v39, v38, v39, vcc
	v_mov_b32_e32 v38, s54
	v_mov_b32_e32 v40, s52
	v_cndmask_b32_e32 v38, v38, v40, vcc
	v_lshlrev_b64 v[36:37], 12, v[36:37]
	v_lshl_add_u64 v[36:37], v[38:39], 0, v[36:37]
	v_lshl_add_u64 v[40:41], v[36:37], 0, v[142:143]
	global_load_dwordx4 v[36:39], v[40:41], off
	global_load_dwordx4 v[176:179], v[40:41], off offset:64
	global_load_dwordx4 v[180:183], v[40:41], off offset:512
	global_load_dwordx4 v[184:187], v[40:41], off offset:576
	v_lshlrev_b64 v[42:43], 11, v[34:35]
	v_lshlrev_b64 v[44:45], 12, v[34:35]
	v_lshl_add_u64 v[42:43], s[10:11], 0, v[42:43]
	v_lshl_add_u64 v[44:45], s[86:87], 0, v[44:45]
	v_lshl_add_u64 v[44:45], v[44:45], 0, v[142:143]
	v_lshl_add_u64 v[42:43], v[138:139], 1, v[42:43]
	v_readlane_b32 s68, v239, 4
	v_readlane_b32 s69, v239, 5
	v_readlane_b32 s70, v239, 6
	v_readlane_b32 s71, v239, 7
	v_readlane_b32 s72, v239, 8
	v_readlane_b32 s73, v239, 9
	v_readlane_b32 s74, v239, 10
	v_readlane_b32 s75, v239, 11
	v_readlane_b32 s76, v239, 12
	v_readlane_b32 s77, v239, 13
	v_readlane_b32 s78, v239, 14
	v_readlane_b32 s79, v239, 15
	s_waitcnt vmcnt(0)
	v_pk_add_f32 v[30:31], v[30:31], v[36:37]
	v_pk_add_f32 v[32:33], v[32:33], v[38:39]
	v_cvt_pk_bf16_f32 v36, v30, v31
	v_cvt_pk_bf16_f32 v37, v32, v33
	global_store_dwordx4 v[44:45], v[30:33], off
	global_store_dwordx2 v[42:43], v[36:37], off
	v_mul_f32_e32 v46, v33, v33
	v_pk_add_f32 v[26:27], v[26:27], v[176:177]
	v_pk_add_f32 v[28:29], v[28:29], v[178:179]
	v_cvt_pk_bf16_f32 v36, v26, v27
	v_cvt_pk_bf16_f32 v37, v28, v29
	global_store_dwordx4 v[44:45], v[26:29], off offset:64
	global_store_dwordx2 v[42:43], v[36:37], off offset:32
	v_pk_add_f32 v[22:23], v[22:23], v[180:181]
	v_pk_add_f32 v[24:25], v[24:25], v[182:183]
	v_cvt_pk_bf16_f32 v36, v22, v23
	v_cvt_pk_bf16_f32 v37, v24, v25
	global_store_dwordx4 v[44:45], v[22:25], off offset:512
	global_store_dwordx2 v[42:43], v[36:37], off offset:256
	v_mul_f32_e32 v40, v31, v31
	v_pk_fma_f32 v[30:31], v[30:31], v[30:31], v[40:41] op_sel_hi:[1,1,0]
	v_mul_f32_e32 v40, v29, v29
	v_pk_fma_f32 v[30:31], v[32:33], v[32:33], v[30:31]
	v_mul_f32_e32 v32, v27, v27
	v_pk_fma_f32 v[26:27], v[26:27], v[26:27], v[32:33] op_sel_hi:[1,1,0]
	v_pk_add_f32 v[30:31], v[46:47], v[30:31] op_sel_hi:[0,1]
	v_pk_fma_f32 v[26:27], v[28:29], v[28:29], v[26:27]
	v_mul_f32_e32 v28, v23, v23
	v_pk_add_f32 v[26:27], v[40:41], v[26:27] op_sel_hi:[0,1]
	v_pk_fma_f32 v[22:23], v[22:23], v[22:23], v[28:29] op_sel_hi:[1,1,0]
	v_pk_add_f32 v[26:27], v[30:31], v[26:27]
	v_mul_f32_e32 v30, v25, v25
	v_pk_fma_f32 v[22:23], v[24:25], v[24:25], v[22:23]
	v_pk_add_f32 v[18:19], v[18:19], v[184:185]
	v_pk_add_f32 v[20:21], v[20:21], v[186:187]
	v_mul_f32_e32 v24, v19, v19
	v_pk_add_f32 v[22:23], v[30:31], v[22:23] op_sel_hi:[0,1]
	global_store_dwordx4 v[44:45], v[18:21], off offset:576
	v_cvt_pk_bf16_f32 v28, v18, v19
	v_pk_add_f32 v[22:23], v[26:27], v[22:23]
	v_pk_fma_f32 v[18:19], v[18:19], v[18:19], v[24:25] op_sel_hi:[1,1,0]
	v_mul_f32_e32 v26, v21, v21
	v_pk_fma_f32 v[18:19], v[20:21], v[20:21], v[18:19]
	v_cvt_pk_bf16_f32 v29, v20, v21
	v_pk_add_f32 v[18:19], v[26:27], v[18:19] op_sel_hi:[0,1]
	v_pk_add_f32 v[18:19], v[22:23], v[18:19]
	global_store_dwordx2 v[42:43], v[28:29], off offset:288
	v_mov_b32_e32 v19, v18
	s_nop 1
	v_permlane16_swap_b32_e32 v18, v19
	v_add_f32_e32 v18, v18, v19
	v_mov_b32_e32 v19, v18
	s_nop 1
	v_permlane32_swap_b32_e32 v18, v19
	s_and_saveexec_b64 s[24:25], s[4:5]
	s_cbranch_execz .LBB0_765
	v_add_f32_e32 v20, v18, v19
	v_lshl_add_u64 v[18:19], v[34:35], 2, s[12:13]
	global_atomic_add_f32 v[18:19], v20, off
;   __device__ __forceinline__ void operator()(const acc8_t& acc, const pg8::Unit& u, int wr, int wc, int fr, int fq) const {
;     ...
;         const int token = (int)EPI_TOKEN(u, ai, m);
;         const float* xr = xrow(p, token);
;         float ss = 0.f;
; #pragma unroll
;         for (int bj = 0; bj < 2; bj++)
; #pragma unroll
;           for (int n = 0; n < 2; n++) {
;             const int f = EPI_COL(u, bj, n);
;             const float4 xv = *(const float4*)(xr + f);
;             const float4 o = make_float4(xv.x + acc[ai][bj][m][n][0], xv.y + acc[ai][bj][m][n][1], xv.z + acc[ai][bj][m][n][2], xv.w + acc[ai][bj][m][n][3]);
;             ss += o.x * o.x + o.y * o.y + o.z * o.z + o.w * o.w;
;             *(float4*)(p.out + O_Y + (size_t)token * 1024 + f) = o;
;             uint2 ob; ob.x = pack2(o.x, o.y); ob.y = pack2(o.z, o.w);
;             *(uint2*)(X1B + (size_t)token * 1024 + f) = ob;
;           }
;         ss = xsum16(ss);
;         ss = xsum32(ss);
;         if (fq == 0) atomicAdd(rss + token, ss);
.LBB0_765:
	s_or_b64 exec, exec, s[24:25]
	v_readlane_b32 s64, v239, 0
	v_readlane_b32 s65, v239, 1
	v_readlane_b32 s66, v239, 2
	v_readlane_b32 s67, v239, 3
	s_mov_b64 s[52:53], s[64:65]
	v_add_u32_e32 v18, 0xb0, v140
	s_mov_b64 s[54:55], s[66:67]
	v_ashrrev_i32_e32 v19, 31, v18
	v_add_u32_e32 v20, 0xffff80b0, v140
	v_cmp_gt_i32_e32 vcc, s57, v18
	v_mov_b32_e32 v22, s55
	v_mov_b32_e32 v23, s53
	v_cndmask_b32_e32 v21, 0, v19, vcc
	v_cndmask_b32_e32 v20, v20, v18, vcc
	v_cndmask_b32_e32 v23, v22, v23, vcc
	v_mov_b32_e32 v22, s54
	v_mov_b32_e32 v24, s52
	v_cndmask_b32_e32 v22, v22, v24, vcc
	v_lshlrev_b64 v[20:21], 12, v[20:21]
	v_lshl_add_u64 v[20:21], v[22:23], 0, v[20:21]
	v_lshl_add_u64 v[24:25], v[20:21], 0, v[142:143]
	global_load_dwordx4 v[20:23], v[24:25], off
	global_load_dwordx4 v[176:179], v[24:25], off offset:64
	global_load_dwordx4 v[180:183], v[24:25], off offset:512
	global_load_dwordx4 v[184:187], v[24:25], off offset:576
	v_lshlrev_b64 v[26:27], 11, v[18:19]
	v_lshlrev_b64 v[28:29], 12, v[18:19]
	v_lshl_add_u64 v[26:27], s[10:11], 0, v[26:27]
	v_lshl_add_u64 v[28:29], s[86:87], 0, v[28:29]
	v_lshl_add_u64 v[28:29], v[28:29], 0, v[142:143]
	v_lshl_add_u64 v[26:27], v[138:139], 1, v[26:27]
	v_readlane_b32 s68, v239, 4
	v_readlane_b32 s69, v239, 5
	v_readlane_b32 s70, v239, 6
	v_readlane_b32 s71, v239, 7
	v_readlane_b32 s72, v239, 8
	v_readlane_b32 s73, v239, 9
	v_readlane_b32 s74, v239, 10
	v_readlane_b32 s75, v239, 11
	v_readlane_b32 s76, v239, 12
	v_readlane_b32 s77, v239, 13
	v_readlane_b32 s78, v239, 14
	v_readlane_b32 s79, v239, 15
	s_waitcnt vmcnt(0)
	v_pk_add_f32 v[14:15], v[14:15], v[20:21]
	v_pk_add_f32 v[16:17], v[16:17], v[22:23]
	v_cvt_pk_bf16_f32 v20, v14, v15
	v_cvt_pk_bf16_f32 v21, v16, v17
	global_store_dwordx4 v[28:29], v[14:17], off
	global_store_dwordx2 v[26:27], v[20:21], off
	v_mul_f32_e32 v30, v17, v17
	v_pk_add_f32 v[10:11], v[10:11], v[176:177]
	v_pk_add_f32 v[12:13], v[12:13], v[178:179]
	v_cvt_pk_bf16_f32 v20, v10, v11
	v_cvt_pk_bf16_f32 v21, v12, v13
	global_store_dwordx4 v[28:29], v[10:13], off offset:64
	global_store_dwordx2 v[26:27], v[20:21], off offset:32
	v_pk_add_f32 v[6:7], v[6:7], v[180:181]
	v_pk_add_f32 v[8:9], v[8:9], v[182:183]
	v_cvt_pk_bf16_f32 v20, v6, v7
	v_cvt_pk_bf16_f32 v21, v8, v9
	global_store_dwordx4 v[28:29], v[6:9], off offset:512
	global_store_dwordx2 v[26:27], v[20:21], off offset:256
	v_mul_f32_e32 v24, v15, v15
	v_pk_fma_f32 v[14:15], v[14:15], v[14:15], v[24:25] op_sel_hi:[1,1,0]
	v_mul_f32_e32 v24, v13, v13
	v_pk_fma_f32 v[14:15], v[16:17], v[16:17], v[14:15]
	v_mul_f32_e32 v16, v11, v11
	v_pk_fma_f32 v[10:11], v[10:11], v[10:11], v[16:17] op_sel_hi:[1,1,0]
	v_pk_add_f32 v[14:15], v[30:31], v[14:15] op_sel_hi:[0,1]
	v_pk_fma_f32 v[10:11], v[12:13], v[12:13], v[10:11]
	v_mul_f32_e32 v12, v7, v7
	v_pk_add_f32 v[10:11], v[24:25], v[10:11] op_sel_hi:[0,1]
	v_pk_fma_f32 v[6:7], v[6:7], v[6:7], v[12:13] op_sel_hi:[1,1,0]
	v_pk_add_f32 v[10:11], v[14:15], v[10:11]
	v_mul_f32_e32 v14, v9, v9
	v_pk_fma_f32 v[6:7], v[8:9], v[8:9], v[6:7]
	v_pk_add_f32 v[2:3], v[2:3], v[184:185]
	v_pk_add_f32 v[4:5], v[4:5], v[186:187]
	v_mul_f32_e32 v8, v3, v3
	v_pk_add_f32 v[6:7], v[14:15], v[6:7] op_sel_hi:[0,1]
	global_store_dwordx4 v[28:29], v[2:5], off offset:576
	v_cvt_pk_bf16_f32 v12, v2, v3
	v_pk_add_f32 v[6:7], v[10:11], v[6:7]
	v_pk_fma_f32 v[2:3], v[2:3], v[2:3], v[8:9] op_sel_hi:[1,1,0]
	v_mul_f32_e32 v10, v5, v5
	v_pk_fma_f32 v[2:3], v[4:5], v[4:5], v[2:3]
	v_cvt_pk_bf16_f32 v13, v4, v5
	v_pk_add_f32 v[2:3], v[10:11], v[2:3] op_sel_hi:[0,1]
	v_pk_add_f32 v[2:3], v[6:7], v[2:3]
	global_store_dwordx2 v[26:27], v[12:13], off offset:288
	v_mov_b32_e32 v3, v2
	s_nop 1
	v_permlane16_swap_b32_e32 v2, v3
	v_add_f32_e32 v2, v2, v3
	v_mov_b32_e32 v3, v2
	s_nop 1
	v_permlane32_swap_b32_e32 v2, v3
	s_and_saveexec_b64 s[24:25], s[4:5]
	s_cbranch_execz .LBB0_743
	v_add_f32_e32 v4, v2, v3
	v_lshl_add_u64 v[2:3], v[18:19], 2, s[12:13]
	global_atomic_add_f32 v[2:3], v4, off
	s_branch .LBB0_743

; #define PG8_STAGE(bufoff, gbase, voff) do { _Pragma("unroll") for (int _i = 0; _i < 2; ++_i) \
;         __builtin_amdgcn_global_load_lds((const unsigned*)((const char*)(gbase) + (voff)[_i]), (PG8_LAS unsigned*)(lds + (bufoff) + ldsw + _i * 8192), 16, 0, 0); } while (0)
; #define PG8_LDA(dst, b, h) do { _Pragma("unroll") for (int m = 0; m < 4; ++m) _Pragma("unroll") for (int k = 0; k < 2; ++k) dst[m][k] = *(const PG8_LAS bf16x8*)(lds + PG8_SA(b, h) + aoff + m * 2048 + k * 1024); } while (0)
; #define PG8_LDB(dst, b, h) do { _Pragma("unroll") for (int n = 0; n < 2; ++n) _Pragma("unroll") for (int k = 0; k < 2; ++k) dst[n][k] = *(const PG8_LAS bf16x8*)(lds + PG8_SB(b, h) + boff + n * 2048 + k * 1024); } while (0)
; #define PG8_MMA(ai, bj, At, Bt) do { __builtin_amdgcn_s_setprio(1); _Pragma("unroll") for (int m = 0; m < 4; ++m) _Pragma("unroll") for (int n = 0; n < 2; ++n) _Pragma("unroll") for (int k = 0; k < 2; ++k) \
;         acc[ai][bj][m][n] = __builtin_amdgcn_mfma_f32_16x16x32_bf16(Bt[n][k], At[m][k], acc[ai][bj][m][n], 0, 0, 0); __builtin_amdgcn_s_setprio(0); } while (0)
; #define PG8_WAIT_L(n) asm volatile("s_waitcnt lgkmcnt(" #n ")" ::: "memory")
; #define PG8_BAR __builtin_amdgcn_s_barrier()
; #define PG8_SCHED __builtin_amdgcn_sched_barrier(0)
; template <class Epi, class Sched>
; __device__ __forceinline__ void gemm_phase(PG8_LAS unsigned char* lds, const Gemm g, const Sched& S, const Epi& E) {
;     ...
;             PG8_LDB(B0, 0, 0); PG8_SCHED; PG8_LDA(At, 0, 0); PG8_STAGE(PG8_SA(1, 1), a1 + hstep, voffA);
;             PG8_WAIT_L(8); PG8_BAR; PG8_WAIT_L(0); PG8_MMA(0, 0, At, B0); PG8_BAR; PG8_SCHED;
;             PG8_LDB(B1, 0, 1); PG8_STAGE(PG8_SB(0, 0), b2, voffB);
;             PG8_BAR; PG8_WAIT_L(0); PG8_MMA(0, 1, At, B1); PG8_BAR;
;             PG8_LDA(At, 0, 1); PG8_STAGE(PG8_SA(0, 0), a2, voffA);
;             PG8_BAR; PG8_WAIT_L(0); PG8_MMA(1, 0, At, B0); PG8_BAR; PG8_SCHED;
.LBB0_828:
	ds_read_b128 v[138:141], v147
	ds_read_b128 v[164:167], v148
	ds_read_b128 v[168:171], v149
	ds_read_b128 v[172:175], v150
	s_add_u32 s24, s22, 0xfff00080
	s_addc_u32 s25, s23, -1
	s_cmp_eq_u32 s54, 60
	s_cselect_b32 s27, s11, s25
	s_cselect_b32 s26, s50, s24
	s_cselect_b32 s25, s9, s53
	s_cselect_b32 s24, s51, s52
	s_mov_b32 m0, s48
	v_lshl_add_u64 v[208:209], s[22:23], 0, v[134:135]
	ds_read_b128 v[176:179], v145
	ds_read_b128 v[180:183], v145 offset:1024
	ds_read_b128 v[184:187], v145 offset:2048
	ds_read_b128 v[188:191], v145 offset:3072
	ds_read_b128 v[192:195], v145 offset:4096
	ds_read_b128 v[196:199], v145 offset:5120
	ds_read_b128 v[200:203], v145 offset:6144
	ds_read_b128 v[204:207], v145 offset:7168
	global_load_lds_dwordx4 v[208:209], off
	v_lshl_add_u64 v[208:209], s[22:23], 0, v[136:137]
	s_mov_b32 m0, s49
	s_nop 0
	global_load_lds_dwordx4 v[208:209], off
	s_waitcnt lgkmcnt(8)
	s_barrier
	s_waitcnt lgkmcnt(0)
	s_setprio 1
	s_waitcnt lgkmcnt(0)
	v_mfma_f32_16x16x32_bf16 v[126:129], v[138:141], v[176:179], v[126:129]
	v_mfma_f32_16x16x32_bf16 v[122:125], v[168:171], v[176:179], v[122:125]
	v_mfma_f32_16x16x32_bf16 v[114:117], v[138:141], v[184:187], v[114:117]
	v_mfma_f32_16x16x32_bf16 v[106:109], v[168:171], v[184:187], v[106:109]
	v_mfma_f32_16x16x32_bf16 v[94:97], v[138:141], v[192:195], v[94:97]
	v_mfma_f32_16x16x32_bf16 v[90:93], v[168:171], v[192:195], v[90:93]
	v_mfma_f32_16x16x32_bf16 v[78:81], v[138:141], v[200:203], v[78:81]
	v_mfma_f32_16x16x32_bf16 v[74:77], v[168:171], v[200:203], v[74:77]
	v_mfma_f32_16x16x32_bf16 v[126:129], v[164:167], v[180:183], v[126:129]
	v_mfma_f32_16x16x32_bf16 v[122:125], v[172:175], v[180:183], v[122:125]
	v_mfma_f32_16x16x32_bf16 v[114:117], v[164:167], v[188:191], v[114:117]
	v_mfma_f32_16x16x32_bf16 v[106:109], v[172:175], v[188:191], v[106:109]
	v_mfma_f32_16x16x32_bf16 v[94:97], v[164:167], v[196:199], v[94:97]
	v_mfma_f32_16x16x32_bf16 v[90:93], v[172:175], v[196:199], v[90:93]
	v_mfma_f32_16x16x32_bf16 v[78:81], v[164:167], v[204:207], v[78:81]
	v_mfma_f32_16x16x32_bf16 v[74:77], v[172:175], v[204:207], v[74:77]
	s_setprio 0
	s_barrier
	s_mov_b32 m0, s19
	v_lshl_add_u64 v[224:225], s[24:25], 0, v[132:133]
	ds_read_b128 v[208:211], v151
	ds_read_b128 v[212:215], v152
	ds_read_b128 v[216:219], v153
	ds_read_b128 v[220:223], v154
	global_load_lds_dwordx4 v[224:225], off
	v_lshl_add_u64 v[226:227], s[24:25], 0, v[130:131]
	s_mov_b32 m0, s21
	s_nop 0
	global_load_lds_dwordx4 v[226:227], off
	s_barrier
	s_waitcnt lgkmcnt(0)
	s_setprio 1
	s_waitcnt lgkmcnt(0)
	v_mfma_f32_16x16x32_bf16 v[118:121], v[208:211], v[176:179], v[118:121]
	v_mfma_f32_16x16x32_bf16 v[110:113], v[216:219], v[176:179], v[110:113]
	v_mfma_f32_16x16x32_bf16 v[102:105], v[208:211], v[184:187], v[102:105]
	v_mfma_f32_16x16x32_bf16 v[98:101], v[216:219], v[184:187], v[98:101]
	v_mfma_f32_16x16x32_bf16 v[86:89], v[208:211], v[192:195], v[86:89]
	v_mfma_f32_16x16x32_bf16 v[82:85], v[216:219], v[192:195], v[82:85]
	v_mfma_f32_16x16x32_bf16 v[70:73], v[208:211], v[200:203], v[70:73]
	v_mfma_f32_16x16x32_bf16 v[66:69], v[216:219], v[200:203], v[66:69]
	v_mfma_f32_16x16x32_bf16 v[118:121], v[212:215], v[180:183], v[118:121]
	v_mfma_f32_16x16x32_bf16 v[110:113], v[220:223], v[180:183], v[110:113]
	v_mfma_f32_16x16x32_bf16 v[102:105], v[212:215], v[188:191], v[102:105]
	v_mfma_f32_16x16x32_bf16 v[98:101], v[220:223], v[188:191], v[98:101]
	v_mfma_f32_16x16x32_bf16 v[86:89], v[212:215], v[196:199], v[86:89]
	v_mfma_f32_16x16x32_bf16 v[82:85], v[220:223], v[196:199], v[82:85]
	v_mfma_f32_16x16x32_bf16 v[70:73], v[212:215], v[204:207], v[70:73]
	v_mfma_f32_16x16x32_bf16 v[66:69], v[220:223], v[204:207], v[66:69]
	s_setprio 0
	s_mov_b32 m0, s35
	v_lshl_add_u64 v[228:229], s[26:27], 0, v[132:133]
	s_barrier
	ds_read_b128 v[176:179], v145 offset:16384
	ds_read_b128 v[180:183], v145 offset:17408
	ds_read_b128 v[184:187], v145 offset:18432
	ds_read_b128 v[188:191], v145 offset:19456
	ds_read_b128 v[192:195], v145 offset:20480
	ds_read_b128 v[196:199], v145 offset:21504
	ds_read_b128 v[200:203], v145 offset:22528
	ds_read_b128 v[204:207], v145 offset:23552
	global_load_lds_dwordx4 v[228:229], off
	v_lshl_add_u64 v[230:231], s[26:27], 0, v[130:131]
	s_mov_b32 m0, s36
	s_nop 0
	global_load_lds_dwordx4 v[230:231], off
	s_barrier
	s_waitcnt lgkmcnt(0)
	s_setprio 1
	s_waitcnt lgkmcnt(0)
	v_mfma_f32_16x16x32_bf16 v[62:65], v[138:141], v[176:179], v[62:65]
	v_mfma_f32_16x16x32_bf16 v[58:61], v[168:171], v[176:179], v[58:61]
	v_mfma_f32_16x16x32_bf16 v[46:49], v[138:141], v[184:187], v[46:49]
	v_mfma_f32_16x16x32_bf16 v[42:45], v[168:171], v[184:187], v[42:45]
	v_mfma_f32_16x16x32_bf16 v[30:33], v[138:141], v[192:195], v[30:33]
	v_mfma_f32_16x16x32_bf16 v[26:29], v[168:171], v[192:195], v[26:29]
	v_mfma_f32_16x16x32_bf16 v[14:17], v[138:141], v[200:203], v[14:17]
	v_mfma_f32_16x16x32_bf16 v[10:13], v[168:171], v[200:203], v[10:13]
	v_mfma_f32_16x16x32_bf16 v[62:65], v[164:167], v[180:183], v[62:65]
	v_mfma_f32_16x16x32_bf16 v[58:61], v[172:175], v[180:183], v[58:61]
	v_mfma_f32_16x16x32_bf16 v[46:49], v[164:167], v[188:191], v[46:49]
	v_mfma_f32_16x16x32_bf16 v[42:45], v[172:175], v[188:191], v[42:45]
	v_mfma_f32_16x16x32_bf16 v[30:33], v[164:167], v[196:199], v[30:33]
	v_mfma_f32_16x16x32_bf16 v[26:29], v[172:175], v[196:199], v[26:29]
	v_mfma_f32_16x16x32_bf16 v[14:17], v[164:167], v[204:207], v[14:17]
	v_mfma_f32_16x16x32_bf16 v[10:13], v[172:175], v[204:207], v[10:13]
	s_setprio 0
	s_barrier
; #define PG8_STAGE(bufoff, gbase, voff) do { _Pragma("unroll") for (int _i = 0; _i < 2; ++_i) \
;         __builtin_amdgcn_global_load_lds((const unsigned*)((const char*)(gbase) + (voff)[_i]), (PG8_LAS unsigned*)(lds + (bufoff) + ldsw + _i * 8192), 16, 0, 0); } while (0)
; #define PG8_LDA(dst, b, h) do { _Pragma("unroll") for (int m = 0; m < 4; ++m) _Pragma("unroll") for (int k = 0; k < 2; ++k) dst[m][k] = *(const PG8_LAS bf16x8*)(lds + PG8_SA(b, h) + aoff + m * 2048 + k * 1024); } while (0)
; #define PG8_LDB(dst, b, h) do { _Pragma("unroll") for (int n = 0; n < 2; ++n) _Pragma("unroll") for (int k = 0; k < 2; ++k) dst[n][k] = *(const PG8_LAS bf16x8*)(lds + PG8_SB(b, h) + boff + n * 2048 + k * 1024); } while (0)
; #define PG8_MMA(ai, bj, At, Bt) do { __builtin_amdgcn_s_setprio(1); _Pragma("unroll") for (int m = 0; m < 4; ++m) _Pragma("unroll") for (int n = 0; n < 2; ++n) _Pragma("unroll") for (int k = 0; k < 2; ++k) \
;         acc[ai][bj][m][n] = __builtin_amdgcn_mfma_f32_16x16x32_bf16(Bt[n][k], At[m][k], acc[ai][bj][m][n], 0, 0, 0); __builtin_amdgcn_s_setprio(0); } while (0)
; #define PG8_WAIT_V(n) asm volatile("s_waitcnt vmcnt(" #n ")" ::: "memory")
; #define PG8_WAIT_L(n) asm volatile("s_waitcnt lgkmcnt(" #n ")" ::: "memory")
; #define PG8_BAR __builtin_amdgcn_s_barrier()
; #define PG8_SCHED __builtin_amdgcn_sched_barrier(0)
; template <class Epi, class Sched>
; __device__ __forceinline__ void gemm_phase(PG8_LAS unsigned char* lds, const Gemm g, const Sched& S, const Epi& E) {
;     ...
;             PG8_STAGE(PG8_SB(0, 1), b2 + hstep, voffB);
;             PG8_WAIT_V(6); PG8_BAR; PG8_MMA(1, 1, At, B1); PG8_BAR;
;             PG8_LDB(B0, 1, 0); PG8_SCHED; PG8_LDA(At, 1, 0); PG8_STAGE(PG8_SA(0, 1), a2 + hstep, voffA);
;             PG8_WAIT_L(8); PG8_BAR; PG8_WAIT_L(0); PG8_MMA(0, 0, At, B0); PG8_BAR; PG8_SCHED;
;             PG8_LDB(B1, 1, 1); PG8_STAGE(PG8_SB(1, 0), b3, voffB);
;             PG8_BAR; PG8_WAIT_L(0); PG8_MMA(0, 1, At, B1); PG8_BAR;
;             PG8_LDA(At, 1, 1); PG8_STAGE(PG8_SA(1, 0), a3, voffA);
	s_add_u32 s56, s24, 0x100000
	s_addc_u32 s57, s25, 0
	s_mov_b32 m0, s37
	v_lshl_add_u64 v[138:139], s[56:57], 0, v[132:133]
	global_load_lds_dwordx4 v[138:139], off
	v_lshl_add_u64 v[138:139], s[56:57], 0, v[130:131]
	s_mov_b32 m0, s38
	s_nop 0
	global_load_lds_dwordx4 v[138:139], off
	s_waitcnt vmcnt(6)
	s_barrier
	s_setprio 1
	v_mfma_f32_16x16x32_bf16 v[54:57], v[208:211], v[176:179], v[54:57]
	v_mfma_f32_16x16x32_bf16 v[50:53], v[216:219], v[176:179], v[50:53]
	v_mfma_f32_16x16x32_bf16 v[38:41], v[208:211], v[184:187], v[38:41]
	v_mfma_f32_16x16x32_bf16 v[34:37], v[216:219], v[184:187], v[34:37]
	v_mfma_f32_16x16x32_bf16 v[22:25], v[208:211], v[192:195], v[22:25]
	v_mfma_f32_16x16x32_bf16 v[18:21], v[216:219], v[192:195], v[18:21]
	v_mfma_f32_16x16x32_bf16 v[6:9], v[208:211], v[200:203], v[6:9]
	v_mfma_f32_16x16x32_bf16 v[2:5], v[216:219], v[200:203], v[2:5]
	v_mfma_f32_16x16x32_bf16 v[54:57], v[212:215], v[180:183], v[54:57]
	v_mfma_f32_16x16x32_bf16 v[50:53], v[220:223], v[180:183], v[50:53]
	v_mfma_f32_16x16x32_bf16 v[38:41], v[212:215], v[188:191], v[38:41]
	v_mfma_f32_16x16x32_bf16 v[34:37], v[220:223], v[188:191], v[34:37]
	v_mfma_f32_16x16x32_bf16 v[22:25], v[212:215], v[196:199], v[22:25]
	v_mfma_f32_16x16x32_bf16 v[18:21], v[220:223], v[196:199], v[18:21]
	v_mfma_f32_16x16x32_bf16 v[6:9], v[212:215], v[204:207], v[6:9]
	v_mfma_f32_16x16x32_bf16 v[2:5], v[220:223], v[204:207], v[2:5]
	s_setprio 0
	s_barrier
	ds_read_b128 v[138:141], v155
	ds_read_b128 v[164:167], v156
	ds_read_b128 v[168:171], v157
	ds_read_b128 v[172:175], v158
	s_add_u32 s26, s26, 0x100000
	s_addc_u32 s27, s27, 0
	s_mov_b32 m0, s39
	v_lshl_add_u64 v[208:209], s[26:27], 0, v[132:133]
	ds_read_b128 v[176:179], v145 offset:32768
	ds_read_b128 v[180:183], v145 offset:33792
	ds_read_b128 v[184:187], v145 offset:34816
	ds_read_b128 v[188:191], v145 offset:35840
	ds_read_b128 v[192:195], v145 offset:36864
	ds_read_b128 v[196:199], v145 offset:37888
	ds_read_b128 v[200:203], v145 offset:38912
	ds_read_b128 v[204:207], v145 offset:39936
	global_load_lds_dwordx4 v[208:209], off
	v_lshl_add_u64 v[208:209], s[26:27], 0, v[130:131]
	s_mov_b32 m0, s40
	s_nop 0
	global_load_lds_dwordx4 v[208:209], off
	s_waitcnt lgkmcnt(8)
	s_barrier
	s_waitcnt lgkmcnt(0)
	s_setprio 1
	s_waitcnt lgkmcnt(0)
	v_mfma_f32_16x16x32_bf16 v[126:129], v[138:141], v[176:179], v[126:129]
	v_mfma_f32_16x16x32_bf16 v[122:125], v[168:171], v[176:179], v[122:125]
	v_mfma_f32_16x16x32_bf16 v[114:117], v[138:141], v[184:187], v[114:117]
	v_mfma_f32_16x16x32_bf16 v[106:109], v[168:171], v[184:187], v[106:109]
	v_mfma_f32_16x16x32_bf16 v[94:97], v[138:141], v[192:195], v[94:97]
	v_mfma_f32_16x16x32_bf16 v[90:93], v[168:171], v[192:195], v[90:93]
	v_mfma_f32_16x16x32_bf16 v[78:81], v[138:141], v[200:203], v[78:81]
	v_mfma_f32_16x16x32_bf16 v[74:77], v[168:171], v[200:203], v[74:77]
	v_mfma_f32_16x16x32_bf16 v[126:129], v[164:167], v[180:183], v[126:129]
	v_mfma_f32_16x16x32_bf16 v[122:125], v[172:175], v[180:183], v[122:125]
	v_mfma_f32_16x16x32_bf16 v[114:117], v[164:167], v[188:191], v[114:117]
	v_mfma_f32_16x16x32_bf16 v[106:109], v[172:175], v[188:191], v[106:109]
	v_mfma_f32_16x16x32_bf16 v[94:97], v[164:167], v[196:199], v[94:97]
	v_mfma_f32_16x16x32_bf16 v[90:93], v[172:175], v[196:199], v[90:93]
	v_mfma_f32_16x16x32_bf16 v[78:81], v[164:167], v[204:207], v[78:81]
	v_mfma_f32_16x16x32_bf16 v[74:77], v[172:175], v[204:207], v[74:77]
	s_setprio 0
	s_barrier
	s_mov_b32 m0, s41
	v_lshl_add_u64 v[224:225], v[224:225], 0, s[6:7]
	ds_read_b128 v[208:211], v159
	ds_read_b128 v[212:215], v160
	ds_read_b128 v[216:219], v161
	ds_read_b128 v[220:223], v162
	global_load_lds_dwordx4 v[224:225], off
	v_lshl_add_u64 v[224:225], v[226:227], 0, s[6:7]
	s_mov_b32 m0, s42
	s_nop 0
	global_load_lds_dwordx4 v[224:225], off
	s_barrier
	s_waitcnt lgkmcnt(0)
	s_setprio 1
	s_waitcnt lgkmcnt(0)
	v_mfma_f32_16x16x32_bf16 v[118:121], v[208:211], v[176:179], v[118:121]
	v_mfma_f32_16x16x32_bf16 v[110:113], v[216:219], v[176:179], v[110:113]
	v_mfma_f32_16x16x32_bf16 v[102:105], v[208:211], v[184:187], v[102:105]
	v_mfma_f32_16x16x32_bf16 v[98:101], v[216:219], v[184:187], v[98:101]
	v_mfma_f32_16x16x32_bf16 v[86:89], v[208:211], v[192:195], v[86:89]
	v_mfma_f32_16x16x32_bf16 v[82:85], v[216:219], v[192:195], v[82:85]
	v_mfma_f32_16x16x32_bf16 v[70:73], v[208:211], v[200:203], v[70:73]
	v_mfma_f32_16x16x32_bf16 v[66:69], v[216:219], v[200:203], v[66:69]
	v_mfma_f32_16x16x32_bf16 v[118:121], v[212:215], v[180:183], v[118:121]
	v_mfma_f32_16x16x32_bf16 v[110:113], v[220:223], v[180:183], v[110:113]
	v_mfma_f32_16x16x32_bf16 v[102:105], v[212:215], v[188:191], v[102:105]
	v_mfma_f32_16x16x32_bf16 v[98:101], v[220:223], v[188:191], v[98:101]
	v_mfma_f32_16x16x32_bf16 v[86:89], v[212:215], v[196:199], v[86:89]
	v_mfma_f32_16x16x32_bf16 v[82:85], v[220:223], v[196:199], v[82:85]
	v_mfma_f32_16x16x32_bf16 v[70:73], v[212:215], v[204:207], v[70:73]
	v_mfma_f32_16x16x32_bf16 v[66:69], v[220:223], v[204:207], v[66:69]
	s_setprio 0
	s_mov_b32 m0, s43
	v_lshl_add_u64 v[224:225], v[228:229], 0, s[6:7]
	s_barrier
	ds_read_b128 v[176:179], v145 offset:49152
	ds_read_b128 v[180:183], v145 offset:50176
	ds_read_b128 v[184:187], v145 offset:51200
	ds_read_b128 v[188:191], v145 offset:52224
	ds_read_b128 v[192:195], v145 offset:53248
	ds_read_b128 v[196:199], v145 offset:54272
	ds_read_b128 v[200:203], v145 offset:55296
	ds_read_b128 v[204:207], v145 offset:56320
	global_load_lds_dwordx4 v[224:225], off
	v_lshl_add_u64 v[224:225], v[230:231], 0, s[6:7]
	s_mov_b32 m0, s44
	s_nop 0
	global_load_lds_dwordx4 v[224:225], off
	s_barrier
; #define PG8_STAGE(bufoff, gbase, voff) do { _Pragma("unroll") for (int _i = 0; _i < 2; ++_i) \
;         __builtin_amdgcn_global_load_lds((const unsigned*)((const char*)(gbase) + (voff)[_i]), (PG8_LAS unsigned*)(lds + (bufoff) + ldsw + _i * 8192), 16, 0, 0); } while (0)
; #define PG8_MMA(ai, bj, At, Bt) do { __builtin_amdgcn_s_setprio(1); _Pragma("unroll") for (int m = 0; m < 4; ++m) _Pragma("unroll") for (int n = 0; n < 2; ++n) _Pragma("unroll") for (int k = 0; k < 2; ++k) \
;         acc[ai][bj][m][n] = __builtin_amdgcn_mfma_f32_16x16x32_bf16(Bt[n][k], At[m][k], acc[ai][bj][m][n], 0, 0, 0); __builtin_amdgcn_s_setprio(0); } while (0)
; #define PG8_WAIT_V(n) asm volatile("s_waitcnt vmcnt(" #n ")" ::: "memory")
; #define PG8_WAIT_L(n) asm volatile("s_waitcnt lgkmcnt(" #n ")" ::: "memory")
; #define PG8_BAR __builtin_amdgcn_s_barrier()
; #define PG8_SCHED __builtin_amdgcn_sched_barrier(0)
; template <class Epi, class Sched>
; __device__ __forceinline__ void gemm_phase(PG8_LAS unsigned char* lds, const Gemm g, const Sched& S, const Epi& E) {
;     ...
;             PG8_BAR; PG8_WAIT_L(0); PG8_MMA(1, 0, At, B0); PG8_BAR; PG8_SCHED;
;             PG8_STAGE(PG8_SB(1, 1), b3 + hstep, voffB);
;             PG8_WAIT_V(6); PG8_BAR; PG8_MMA(1, 1, At, B1); PG8_BAR;
;   __device__ __forceinline__ void operator()(const acc8_t& acc, const pg8::Unit& u, int wr, int wc, int fr, int fq) const {
; #pragma unroll
;     for (int ai = 0; ai < 2; ai++)
; #pragma unroll
;       for (int m = 0; m < 4; m++) {
;         const size_t token = EPI_TOKEN(u, ai, m);
; #pragma unroll
;         for (int bj = 0; bj < 2; bj++)
; #pragma unroll
;           for (int n = 0; n < 2; n++) {
;             float* yp = out + O_Y + token * 1024 + EPI_COL(u, bj, n);
;             float4 y = *(const float4*)yp;
;             y.x += acc[ai][bj][m][n][0]; y.y += acc[ai][bj][m][n][1]; y.z += acc[ai][bj][m][n][2]; y.w += acc[ai][bj][m][n][3];
;             *(float4*)yp = y;
;           }
;       }
;   }
	s_waitcnt lgkmcnt(0)
	s_setprio 1
	s_waitcnt lgkmcnt(0)
	v_mfma_f32_16x16x32_bf16 v[62:65], v[138:141], v[176:179], v[62:65]
	v_mfma_f32_16x16x32_bf16 v[58:61], v[168:171], v[176:179], v[58:61]
	v_mfma_f32_16x16x32_bf16 v[46:49], v[138:141], v[184:187], v[46:49]
	v_mfma_f32_16x16x32_bf16 v[42:45], v[168:171], v[184:187], v[42:45]
	v_mfma_f32_16x16x32_bf16 v[30:33], v[138:141], v[192:195], v[30:33]
	v_mfma_f32_16x16x32_bf16 v[26:29], v[168:171], v[192:195], v[26:29]
	v_mfma_f32_16x16x32_bf16 v[14:17], v[138:141], v[200:203], v[14:17]
	v_mfma_f32_16x16x32_bf16 v[10:13], v[168:171], v[200:203], v[10:13]
	v_mfma_f32_16x16x32_bf16 v[62:65], v[164:167], v[180:183], v[62:65]
	v_mfma_f32_16x16x32_bf16 v[58:61], v[172:175], v[180:183], v[58:61]
	v_mfma_f32_16x16x32_bf16 v[46:49], v[164:167], v[188:191], v[46:49]
	v_mfma_f32_16x16x32_bf16 v[42:45], v[172:175], v[188:191], v[42:45]
	v_mfma_f32_16x16x32_bf16 v[30:33], v[164:167], v[196:199], v[30:33]
	v_mfma_f32_16x16x32_bf16 v[26:29], v[172:175], v[196:199], v[26:29]
	v_mfma_f32_16x16x32_bf16 v[14:17], v[164:167], v[204:207], v[14:17]
	v_mfma_f32_16x16x32_bf16 v[10:13], v[172:175], v[204:207], v[10:13]
	s_setprio 0
	s_barrier
	s_add_u32 s24, s24, 0x100080
	s_addc_u32 s25, s25, 0
	s_mov_b32 m0, s45
	v_lshl_add_u64 v[138:139], s[24:25], 0, v[132:133]
	global_load_lds_dwordx4 v[138:139], off
	v_lshl_add_u64 v[138:139], s[24:25], 0, v[130:131]
	s_mov_b32 m0, s46
	s_nop 0
	global_load_lds_dwordx4 v[138:139], off
	s_waitcnt vmcnt(6)
	s_barrier
	s_setprio 1
	v_mfma_f32_16x16x32_bf16 v[54:57], v[208:211], v[176:179], v[54:57]
	v_mfma_f32_16x16x32_bf16 v[50:53], v[216:219], v[176:179], v[50:53]
	v_mfma_f32_16x16x32_bf16 v[38:41], v[208:211], v[184:187], v[38:41]
	v_mfma_f32_16x16x32_bf16 v[34:37], v[216:219], v[184:187], v[34:37]
	v_mfma_f32_16x16x32_bf16 v[22:25], v[208:211], v[192:195], v[22:25]
	v_mfma_f32_16x16x32_bf16 v[18:21], v[216:219], v[192:195], v[18:21]
	v_mfma_f32_16x16x32_bf16 v[6:9], v[208:211], v[200:203], v[6:9]
	v_mfma_f32_16x16x32_bf16 v[2:5], v[216:219], v[200:203], v[2:5]
	v_mfma_f32_16x16x32_bf16 v[54:57], v[212:215], v[180:183], v[54:57]
	v_mfma_f32_16x16x32_bf16 v[50:53], v[220:223], v[180:183], v[50:53]
	v_mfma_f32_16x16x32_bf16 v[38:41], v[212:215], v[188:191], v[38:41]
	v_mfma_f32_16x16x32_bf16 v[34:37], v[220:223], v[188:191], v[34:37]
	v_mfma_f32_16x16x32_bf16 v[22:25], v[212:215], v[196:199], v[22:25]
	v_mfma_f32_16x16x32_bf16 v[18:21], v[220:223], v[196:199], v[18:21]
	v_mfma_f32_16x16x32_bf16 v[6:9], v[212:215], v[204:207], v[6:9]
	v_mfma_f32_16x16x32_bf16 v[2:5], v[220:223], v[204:207], v[2:5]
	s_setprio 0
	s_add_i32 s54, s54, 2
	s_add_u32 s22, s22, 0x100
	s_addc_u32 s23, s23, 0
	s_add_u32 s52, s52, 0x100
	s_addc_u32 s53, s53, 0
	s_cmp_gt_u32 s54, 61
	s_barrier
	s_cbranch_scc0 .LBB0_828
	v_lshl_add_u32 v140, s20, 8, v144
	v_lshl_or_b32 v138, s18, 8, v146
	v_ashrrev_i32_e32 v141, 31, v140
	v_lshlrev_b64 v[164:165], 12, v[140:141]
	v_ashrrev_i32_e32 v139, 31, v138
	v_lshl_add_u64 v[164:165], s[86:87], 0, v[164:165]
	v_lshlrev_b64 v[138:139], 2, v[138:139]
	v_lshl_add_u64 v[168:169], v[164:165], 0, v[138:139]
	global_load_dwordx4 v[164:167], v[168:169], off
	global_load_dwordx4 v[176:179], v[168:169], off offset:64
	global_load_dwordx4 v[180:183], v[168:169], off offset:512
	global_load_dwordx4 v[184:187], v[168:169], off offset:576
	s_and_b64 vcc, exec, s[12:13]
	s_mov_b32 s18, s8
	s_mov_b32 s20, s10
	s_mov_b64 s[24:25], s[16:17]
	s_mov_b64 s[22:23], s[14:15]
	s_waitcnt vmcnt(0)
	v_pk_add_f32 v[126:127], v[126:127], v[164:165]
	v_pk_add_f32 v[128:129], v[128:129], v[166:167]
	global_store_dwordx4 v[168:169], v[126:129], off
	v_pk_add_f32 v[122:123], v[122:123], v[176:177]
	v_pk_add_f32 v[124:125], v[124:125], v[178:179]
	global_store_dwordx4 v[168:169], v[122:125], off offset:64
	v_pk_add_f32 v[118:119], v[118:119], v[180:181]
	v_pk_add_f32 v[120:121], v[120:121], v[182:183]
	global_store_dwordx4 v[168:169], v[118:121], off offset:512
	v_pk_add_f32 v[110:111], v[110:111], v[184:185]
	v_pk_add_f32 v[112:113], v[112:113], v[186:187]
	global_store_dwordx4 v[168:169], v[110:113], off offset:576
	s_nop 1
	v_or_b32_e32 v110, 16, v140
	v_ashrrev_i32_e32 v111, 31, v110
	v_lshlrev_b64 v[110:111], 12, v[110:111]
	v_lshl_add_u64 v[110:111], s[86:87], 0, v[110:111]
	v_lshl_add_u64 v[118:119], v[110:111], 0, v[138:139]
	global_load_dwordx4 v[110:113], v[118:119], off
	global_load_dwordx4 v[176:179], v[118:119], off offset:64
	global_load_dwordx4 v[180:183], v[118:119], off offset:512
	global_load_dwordx4 v[184:187], v[118:119], off offset:576
	s_waitcnt vmcnt(3)
	v_pk_add_f32 v[110:111], v[114:115], v[110:111]
	v_pk_add_f32 v[112:113], v[116:117], v[112:113]
	global_store_dwordx4 v[118:119], v[110:113], off
	s_waitcnt vmcnt(3)
	v_pk_add_f32 v[106:107], v[106:107], v[176:177]
	v_pk_add_f32 v[108:109], v[108:109], v[178:179]
	global_store_dwordx4 v[118:119], v[106:109], off offset:64
	s_waitcnt vmcnt(3)
	v_pk_add_f32 v[102:103], v[102:103], v[180:181]
	v_pk_add_f32 v[104:105], v[104:105], v[182:183]
	global_store_dwordx4 v[118:119], v[102:105], off offset:512
	s_waitcnt vmcnt(3)
	v_pk_add_f32 v[98:99], v[98:99], v[184:185]
	v_pk_add_f32 v[100:101], v[100:101], v[186:187]
	global_store_dwordx4 v[118:119], v[98:101], off offset:576
	s_nop 1
	v_or_b32_e32 v98, 32, v140
	v_ashrrev_i32_e32 v99, 31, v98
	v_lshlrev_b64 v[98:99], 12, v[98:99]
	v_lshl_add_u64 v[98:99], s[86:87], 0, v[98:99]
	v_lshl_add_u64 v[102:103], v[98:99], 0, v[138:139]
	global_load_dwordx4 v[98:101], v[102:103], off
	global_load_dwordx4 v[176:179], v[102:103], off offset:64
	global_load_dwordx4 v[180:183], v[102:103], off offset:512
	global_load_dwordx4 v[184:187], v[102:103], off offset:576
	s_waitcnt vmcnt(3)
;   __device__ __forceinline__ void operator()(const acc8_t& acc, const pg8::Unit& u, int wr, int wc, int fr, int fq) const {
; #pragma unroll
;     for (int ai = 0; ai < 2; ai++)
; #pragma unroll
;       for (int m = 0; m < 4; m++) {
;         const size_t token = EPI_TOKEN(u, ai, m);
; #pragma unroll
;         for (int bj = 0; bj < 2; bj++)
; #pragma unroll
;           for (int n = 0; n < 2; n++) {
;             float* yp = out + O_Y + token * 1024 + EPI_COL(u, bj, n);
;             float4 y = *(const float4*)yp;
;             y.x += acc[ai][bj][m][n][0]; y.y += acc[ai][bj][m][n][1]; y.z += acc[ai][bj][m][n][2]; y.w += acc[ai][bj][m][n][3];
;             *(float4*)yp = y;
;           }
;       }
;   }
	v_pk_add_f32 v[94:95], v[94:95], v[98:99]
	v_pk_add_f32 v[96:97], v[96:97], v[100:101]
	global_store_dwordx4 v[102:103], v[94:97], off
	s_waitcnt vmcnt(3)
	v_pk_add_f32 v[90:91], v[90:91], v[176:177]
	v_pk_add_f32 v[92:93], v[92:93], v[178:179]
	global_store_dwordx4 v[102:103], v[90:93], off offset:64
	s_waitcnt vmcnt(3)
	v_pk_add_f32 v[86:87], v[86:87], v[180:181]
	v_pk_add_f32 v[88:89], v[88:89], v[182:183]
	global_store_dwordx4 v[102:103], v[86:89], off offset:512
	s_waitcnt vmcnt(3)
	v_pk_add_f32 v[82:83], v[82:83], v[184:185]
	v_pk_add_f32 v[84:85], v[84:85], v[186:187]
	global_store_dwordx4 v[102:103], v[82:85], off offset:576
	s_nop 1
	v_or_b32_e32 v82, 48, v140
	v_ashrrev_i32_e32 v83, 31, v82
	v_lshlrev_b64 v[82:83], 12, v[82:83]
	v_lshl_add_u64 v[82:83], s[86:87], 0, v[82:83]
	v_lshl_add_u64 v[86:87], v[82:83], 0, v[138:139]
	global_load_dwordx4 v[82:85], v[86:87], off
	global_load_dwordx4 v[176:179], v[86:87], off offset:64
	global_load_dwordx4 v[180:183], v[86:87], off offset:512
	global_load_dwordx4 v[184:187], v[86:87], off offset:576
	s_waitcnt vmcnt(3)
	v_pk_add_f32 v[78:79], v[78:79], v[82:83]
	v_pk_add_f32 v[80:81], v[80:81], v[84:85]
	global_store_dwordx4 v[86:87], v[78:81], off
	s_waitcnt vmcnt(3)
	v_pk_add_f32 v[74:75], v[74:75], v[176:177]
	v_pk_add_f32 v[76:77], v[76:77], v[178:179]
	global_store_dwordx4 v[86:87], v[74:77], off offset:64
	s_waitcnt vmcnt(3)
	v_pk_add_f32 v[70:71], v[70:71], v[180:181]
	v_pk_add_f32 v[72:73], v[72:73], v[182:183]
	global_store_dwordx4 v[86:87], v[70:73], off offset:512
	s_waitcnt vmcnt(3)
	v_pk_add_f32 v[66:67], v[66:67], v[184:185]
	v_pk_add_f32 v[68:69], v[68:69], v[186:187]
	global_store_dwordx4 v[86:87], v[66:69], off offset:576
	s_nop 1
	v_add_u32_e32 v66, 0x80, v140
	v_ashrrev_i32_e32 v67, 31, v66
	v_lshlrev_b64 v[66:67], 12, v[66:67]
	v_lshl_add_u64 v[66:67], s[86:87], 0, v[66:67]
	v_lshl_add_u64 v[70:71], v[66:67], 0, v[138:139]
	global_load_dwordx4 v[66:69], v[70:71], off
	global_load_dwordx4 v[176:179], v[70:71], off offset:64
	global_load_dwordx4 v[180:183], v[70:71], off offset:512
	global_load_dwordx4 v[184:187], v[70:71], off offset:576
	s_waitcnt vmcnt(3)
	v_pk_add_f32 v[62:63], v[62:63], v[66:67]
	v_pk_add_f32 v[64:65], v[64:65], v[68:69]
	global_store_dwordx4 v[70:71], v[62:65], off
	s_waitcnt vmcnt(3)
	v_pk_add_f32 v[58:59], v[58:59], v[176:177]
	v_pk_add_f32 v[60:61], v[60:61], v[178:179]
	global_store_dwordx4 v[70:71], v[58:61], off offset:64
	s_waitcnt vmcnt(3)
	v_pk_add_f32 v[54:55], v[54:55], v[180:181]
	v_pk_add_f32 v[56:57], v[56:57], v[182:183]
	global_store_dwordx4 v[70:71], v[54:57], off offset:512
	s_waitcnt vmcnt(3)
	v_pk_add_f32 v[50:51], v[50:51], v[184:185]
	v_pk_add_f32 v[52:53], v[52:53], v[186:187]
	global_store_dwordx4 v[70:71], v[50:53], off offset:576
	s_nop 1
	v_add_u32_e32 v50, 0x90, v140
	v_ashrrev_i32_e32 v51, 31, v50
	v_lshlrev_b64 v[50:51], 12, v[50:51]
	v_lshl_add_u64 v[50:51], s[86:87], 0, v[50:51]
	v_lshl_add_u64 v[54:55], v[50:51], 0, v[138:139]
	global_load_dwordx4 v[50:53], v[54:55], off
	global_load_dwordx4 v[176:179], v[54:55], off offset:64
	global_load_dwordx4 v[180:183], v[54:55], off offset:512
	global_load_dwordx4 v[184:187], v[54:55], off offset:576
	s_waitcnt vmcnt(3)
	v_pk_add_f32 v[46:47], v[46:47], v[50:51]
	v_pk_add_f32 v[48:49], v[48:49], v[52:53]
	global_store_dwordx4 v[54:55], v[46:49], off
	s_waitcnt vmcnt(3)
	v_pk_add_f32 v[42:43], v[42:43], v[176:177]
	v_pk_add_f32 v[44:45], v[44:45], v[178:179]
	global_store_dwordx4 v[54:55], v[42:45], off offset:64
	s_waitcnt vmcnt(3)
	v_pk_add_f32 v[38:39], v[38:39], v[180:181]
	v_pk_add_f32 v[40:41], v[40:41], v[182:183]
	global_store_dwordx4 v[54:55], v[38:41], off offset:512
	s_waitcnt vmcnt(3)
	v_pk_add_f32 v[34:35], v[34:35], v[184:185]
	v_pk_add_f32 v[36:37], v[36:37], v[186:187]
	global_store_dwordx4 v[54:55], v[34:37], off offset:576
	s_nop 1
	v_add_u32_e32 v34, 0xa0, v140
	v_ashrrev_i32_e32 v35, 31, v34
	v_lshlrev_b64 v[34:35], 12, v[34:35]
	v_lshl_add_u64 v[34:35], s[86:87], 0, v[34:35]
	v_lshl_add_u64 v[38:39], v[34:35], 0, v[138:139]
	global_load_dwordx4 v[34:37], v[38:39], off
	global_load_dwordx4 v[176:179], v[38:39], off offset:64
	global_load_dwordx4 v[180:183], v[38:39], off offset:512
	global_load_dwordx4 v[184:187], v[38:39], off offset:576
	s_waitcnt vmcnt(3)
	v_pk_add_f32 v[30:31], v[30:31], v[34:35]
	v_pk_add_f32 v[32:33], v[32:33], v[36:37]
	global_store_dwordx4 v[38:39], v[30:33], off
	s_waitcnt vmcnt(3)
	v_pk_add_f32 v[26:27], v[26:27], v[176:177]
	v_pk_add_f32 v[28:29], v[28:29], v[178:179]
	global_store_dwordx4 v[38:39], v[26:29], off offset:64
	s_waitcnt vmcnt(3)
	v_pk_add_f32 v[22:23], v[22:23], v[180:181]
	v_pk_add_f32 v[24:25], v[24:25], v[182:183]
	global_store_dwordx4 v[38:39], v[22:25], off offset:512
	s_waitcnt vmcnt(3)
	v_pk_add_f32 v[18:19], v[18:19], v[184:185]
	v_pk_add_f32 v[20:21], v[20:21], v[186:187]
	global_store_dwordx4 v[38:39], v[18:21], off offset:576
	s_nop 1
	v_add_u32_e32 v18, 0xb0, v140
	v_ashrrev_i32_e32 v19, 31, v18
	v_lshlrev_b64 v[18:19], 12, v[18:19]
	v_lshl_add_u64 v[18:19], s[86:87], 0, v[18:19]
	v_lshl_add_u64 v[22:23], v[18:19], 0, v[138:139]
	global_load_dwordx4 v[18:21], v[22:23], off
	global_load_dwordx4 v[176:179], v[22:23], off offset:64
	global_load_dwordx4 v[180:183], v[22:23], off offset:512
	global_load_dwordx4 v[184:187], v[22:23], off offset:576
	s_waitcnt vmcnt(3)
	v_pk_add_f32 v[14:15], v[14:15], v[18:19]
	v_pk_add_f32 v[16:17], v[16:17], v[20:21]
	global_store_dwordx4 v[22:23], v[14:17], off
	s_waitcnt vmcnt(3)
	v_pk_add_f32 v[10:11], v[10:11], v[176:177]
	v_pk_add_f32 v[12:13], v[12:13], v[178:179]
	global_store_dwordx4 v[22:23], v[10:13], off offset:64
	s_waitcnt vmcnt(3)
	v_pk_add_f32 v[6:7], v[6:7], v[180:181]
	v_pk_add_f32 v[8:9], v[8:9], v[182:183]
	global_store_dwordx4 v[22:23], v[6:9], off offset:512
	s_waitcnt vmcnt(3)
	v_pk_add_f32 v[2:3], v[2:3], v[184:185]
	v_pk_add_f32 v[4:5], v[4:5], v[186:187]
	global_store_dwordx4 v[22:23], v[2:5], off offset:576
	s_cbranch_vccz .LBB0_825
	s_waitcnt vmcnt(0)
	s_cmpk_gt_u32 s34, 0xff
	s_cbranch_scc1 .LBB0_832
	s_barrier
